# PROJ's A operand (normalised activations from the prep norm phase and the DOWN epilogue) also k-blocked
# speedup vs baseline: 1.1175x; 1.0013x over previous
.Lgm2_loop:
	v_add_u32_e32 v248, s30, v155
	v_add_u32_e32 v249, s30, v160
	v_mfma_f32_16x16x32_bf16 v[128:131], v[212:215], v[186:189], v[128:131]
	ds_read_b128 v[0:3], v248
	v_mfma_f32_16x16x32_bf16 v[68:71], v[212:215], v[190:193], v[68:71]
	ds_read_b128 v[16:19], v249 offset:8192
	v_mfma_f32_16x16x32_bf16 v[108:111], v[212:215], v[194:197], v[108:111]
	ds_read_b128 v[4:7], v248 offset:1024
	v_mfma_f32_16x16x32_bf16 v[132:135], v[212:215], v[208:211], v[132:135]
	ds_read_b128 v[20:23], v249 offset:9216
	v_mfma_f32_16x16x32_bf16 v[120:123], v[216:219], v[186:189], v[120:123]
	ds_read_b128 v[8:11], v248 offset:2048
	v_mfma_f32_16x16x32_bf16 v[64:67], v[216:219], v[190:193], v[64:67]
	ds_read_b128 v[162:165], v249 offset:10240
	v_mfma_f32_16x16x32_bf16 v[112:115], v[216:219], v[194:197], v[112:115]
	ds_read_b128 v[12:15], v248 offset:3072
	v_mfma_f32_16x16x32_bf16 v[136:139], v[216:219], v[208:211], v[136:139]
	ds_read_b128 v[166:169], v249 offset:11264
	v_mfma_f32_16x16x32_bf16 v[104:107], v[220:223], v[186:189], v[104:107]
	ds_read_b128 v[170:173], v249 offset:12288
	v_mfma_f32_16x16x32_bf16 v[56:59], v[220:223], v[190:193], v[56:59]
	ds_read_b128 v[174:177], v249 offset:13312
	v_mfma_f32_16x16x32_bf16 v[116:119], v[220:223], v[194:197], v[116:119]
	ds_read_b128 v[178:181], v249 offset:14336
	v_mfma_f32_16x16x32_bf16 v[140:143], v[220:223], v[208:211], v[140:143]
	ds_read_b128 v[182:185], v249 offset:15360
	s_add_u32 m0, s25, s24
	v_mfma_f32_16x16x32_bf16 v[100:103], v[224:227], v[186:189], v[100:103]
	global_load_lds_dwordx4 v156, s[26:27]
	v_mfma_f32_16x16x32_bf16 v[52:55], v[224:227], v[190:193], v[52:55]
	v_mfma_f32_16x16x32_bf16 v[124:127], v[224:227], v[194:197], v[124:127]
	s_add_u32 m0, m0, 0x1000
	v_mfma_f32_16x16x32_bf16 v[144:147], v[224:227], v[208:211], v[144:147]
	global_load_lds_dwordx4 v157, s[26:27]
	v_mfma_f32_16x16x32_bf16 v[60:63], v[228:231], v[186:189], v[60:63]
	v_mfma_f32_16x16x32_bf16 v[36:39], v[228:231], v[190:193], v[36:39]
	s_add_u32 m0, m0, 0x1000
	v_mfma_f32_16x16x32_bf16 v[80:83], v[228:231], v[194:197], v[80:83]
	global_load_lds_dwordx4 v156, s[28:29]
	v_mfma_f32_16x16x32_bf16 v[92:95], v[228:231], v[208:211], v[92:95]
	v_mfma_f32_16x16x32_bf16 v[48:51], v[232:235], v[186:189], v[48:51]
	s_add_u32 m0, m0, 0x1000
	v_mfma_f32_16x16x32_bf16 v[32:35], v[232:235], v[190:193], v[32:35]
	global_load_lds_dwordx4 v157, s[28:29]
	v_mfma_f32_16x16x32_bf16 v[84:87], v[232:235], v[194:197], v[84:87]
	v_mfma_f32_16x16x32_bf16 v[88:91], v[232:235], v[208:211], v[88:91]
	s_add_u32 m0, m0, 0x1000
	v_mfma_f32_16x16x32_bf16 v[44:47], v[236:239], v[186:189], v[44:47]
	global_load_lds_dwordx4 v158, s[28:29]
	v_mfma_f32_16x16x32_bf16 v[28:31], v[236:239], v[190:193], v[28:31]
	v_mfma_f32_16x16x32_bf16 v[96:99], v[236:239], v[194:197], v[96:99]
	s_add_u32 m0, m0, 0x1000
	v_mfma_f32_16x16x32_bf16 v[76:79], v[236:239], v[208:211], v[76:79]
	global_load_lds_dwordx4 v159, s[28:29]
	v_mfma_f32_16x16x32_bf16 v[40:43], v[240:243], v[186:189], v[40:43]
	v_mfma_f32_16x16x32_bf16 v[24:27], v[240:243], v[190:193], v[24:27]
	v_mfma_f32_16x16x32_bf16 v[72:75], v[240:243], v[194:197], v[72:75]
	v_mfma_f32_16x16x32_bf16 v[148:151], v[240:243], v[208:211], v[148:151]
	s_add_u32 s26, s26, 0x200000
	s_addc_u32 s27, s27, 0
	s_add_u32 s28, s28, 0x10000
	s_addc_u32 s29, s29, 0
	s_add_u32 s25, s25, 24576
	s_cmp_eq_u32 s25, 73728
	s_cselect_b32 s25, 0, s25
	s_add_u32 s30, s30, 24576
	s_cmp_eq_u32 s30, 73728
	s_cselect_b32 s30, 0, s30
	s_waitcnt vmcnt(6)
	s_waitcnt lgkmcnt(0)
	s_barrier
	v_add_u32_e32 v248, s30, v155
	v_add_u32_e32 v249, s30, v160
	v_mfma_f32_16x16x32_bf16 v[128:131], v[16:19], v[0:3], v[128:131]
	ds_read_b128 v[186:189], v248
	v_mfma_f32_16x16x32_bf16 v[68:71], v[16:19], v[4:7], v[68:71]
	ds_read_b128 v[212:215], v249 offset:8192
	v_mfma_f32_16x16x32_bf16 v[108:111], v[16:19], v[8:11], v[108:111]
	ds_read_b128 v[190:193], v248 offset:1024
	v_mfma_f32_16x16x32_bf16 v[132:135], v[16:19], v[12:15], v[132:135]
	ds_read_b128 v[216:219], v249 offset:9216
	v_mfma_f32_16x16x32_bf16 v[120:123], v[20:23], v[0:3], v[120:123]
	ds_read_b128 v[194:197], v248 offset:2048
	v_mfma_f32_16x16x32_bf16 v[64:67], v[20:23], v[4:7], v[64:67]
	ds_read_b128 v[220:223], v249 offset:10240
	v_mfma_f32_16x16x32_bf16 v[112:115], v[20:23], v[8:11], v[112:115]
	ds_read_b128 v[208:211], v248 offset:3072
	v_mfma_f32_16x16x32_bf16 v[136:139], v[20:23], v[12:15], v[136:139]
	ds_read_b128 v[224:227], v249 offset:11264
	v_mfma_f32_16x16x32_bf16 v[104:107], v[162:165], v[0:3], v[104:107]
	ds_read_b128 v[228:231], v249 offset:12288
	v_mfma_f32_16x16x32_bf16 v[56:59], v[162:165], v[4:7], v[56:59]
	ds_read_b128 v[232:235], v249 offset:13312
	v_mfma_f32_16x16x32_bf16 v[116:119], v[162:165], v[8:11], v[116:119]
	ds_read_b128 v[236:239], v249 offset:14336
	v_mfma_f32_16x16x32_bf16 v[140:143], v[162:165], v[12:15], v[140:143]
	ds_read_b128 v[240:243], v249 offset:15360
	s_add_u32 m0, s25, s24
	v_mfma_f32_16x16x32_bf16 v[100:103], v[166:169], v[0:3], v[100:103]
	global_load_lds_dwordx4 v156, s[26:27]
	v_mfma_f32_16x16x32_bf16 v[52:55], v[166:169], v[4:7], v[52:55]
	v_mfma_f32_16x16x32_bf16 v[124:127], v[166:169], v[8:11], v[124:127]
	s_add_u32 m0, m0, 0x1000
	v_mfma_f32_16x16x32_bf16 v[144:147], v[166:169], v[12:15], v[144:147]
	global_load_lds_dwordx4 v157, s[26:27]
	v_mfma_f32_16x16x32_bf16 v[60:63], v[170:173], v[0:3], v[60:63]
	v_mfma_f32_16x16x32_bf16 v[36:39], v[170:173], v[4:7], v[36:39]
	s_add_u32 m0, m0, 0x1000
	v_mfma_f32_16x16x32_bf16 v[80:83], v[170:173], v[8:11], v[80:83]
	global_load_lds_dwordx4 v156, s[28:29]
	v_mfma_f32_16x16x32_bf16 v[92:95], v[170:173], v[12:15], v[92:95]
	v_mfma_f32_16x16x32_bf16 v[48:51], v[174:177], v[0:3], v[48:51]
	s_add_u32 m0, m0, 0x1000
	v_mfma_f32_16x16x32_bf16 v[32:35], v[174:177], v[4:7], v[32:35]
	global_load_lds_dwordx4 v157, s[28:29]
	v_mfma_f32_16x16x32_bf16 v[84:87], v[174:177], v[8:11], v[84:87]
	v_mfma_f32_16x16x32_bf16 v[88:91], v[174:177], v[12:15], v[88:91]
	s_add_u32 m0, m0, 0x1000
	v_mfma_f32_16x16x32_bf16 v[44:47], v[178:181], v[0:3], v[44:47]
	global_load_lds_dwordx4 v158, s[28:29]
	v_mfma_f32_16x16x32_bf16 v[28:31], v[178:181], v[4:7], v[28:31]
	v_mfma_f32_16x16x32_bf16 v[96:99], v[178:181], v[8:11], v[96:99]
	s_add_u32 m0, m0, 0x1000
	v_mfma_f32_16x16x32_bf16 v[76:79], v[178:181], v[12:15], v[76:79]
	global_load_lds_dwordx4 v159, s[28:29]
	v_mfma_f32_16x16x32_bf16 v[40:43], v[182:185], v[0:3], v[40:43]
	v_mfma_f32_16x16x32_bf16 v[24:27], v[182:185], v[4:7], v[24:27]
	v_mfma_f32_16x16x32_bf16 v[72:75], v[182:185], v[8:11], v[72:75]
	v_mfma_f32_16x16x32_bf16 v[148:151], v[182:185], v[12:15], v[148:151]
	s_add_u32 s26, s26, 0x200000
	s_addc_u32 s27, s27, 0
	s_add_u32 s28, s28, 0x10000
	s_addc_u32 s29, s29, 0
	s_add_u32 s25, s25, 24576
	s_cmp_eq_u32 s25, 73728
	s_cselect_b32 s25, 0, s25
	s_add_u32 s30, s30, 24576
	s_cmp_eq_u32 s30, 73728
	s_cselect_b32 s30, 0, s30
	s_waitcnt vmcnt(6)
	s_waitcnt lgkmcnt(0)
	s_barrier
	s_sub_u32 s31, s31, 1
	s_cmp_lg_u32 s31, 0
	s_cbranch_scc1 .Lgm2_loop
	v_add_u32_e32 v248, s30, v155
	v_add_u32_e32 v249, s30, v160
	v_mfma_f32_16x16x32_bf16 v[128:131], v[212:215], v[186:189], v[128:131]
	ds_read_b128 v[0:3], v248
	v_mfma_f32_16x16x32_bf16 v[68:71], v[212:215], v[190:193], v[68:71]
	ds_read_b128 v[16:19], v249 offset:8192
	v_mfma_f32_16x16x32_bf16 v[108:111], v[212:215], v[194:197], v[108:111]
	ds_read_b128 v[4:7], v248 offset:1024
	v_mfma_f32_16x16x32_bf16 v[132:135], v[212:215], v[208:211], v[132:135]
	ds_read_b128 v[20:23], v249 offset:9216
	v_mfma_f32_16x16x32_bf16 v[120:123], v[216:219], v[186:189], v[120:123]
	ds_read_b128 v[8:11], v248 offset:2048
	v_mfma_f32_16x16x32_bf16 v[64:67], v[216:219], v[190:193], v[64:67]
	ds_read_b128 v[162:165], v249 offset:10240
	v_mfma_f32_16x16x32_bf16 v[112:115], v[216:219], v[194:197], v[112:115]
	ds_read_b128 v[12:15], v248 offset:3072
	v_mfma_f32_16x16x32_bf16 v[136:139], v[216:219], v[208:211], v[136:139]
	ds_read_b128 v[166:169], v249 offset:11264
	v_mfma_f32_16x16x32_bf16 v[104:107], v[220:223], v[186:189], v[104:107]
	ds_read_b128 v[170:173], v249 offset:12288
	v_mfma_f32_16x16x32_bf16 v[56:59], v[220:223], v[190:193], v[56:59]
	ds_read_b128 v[174:177], v249 offset:13312
	v_mfma_f32_16x16x32_bf16 v[116:119], v[220:223], v[194:197], v[116:119]
	ds_read_b128 v[178:181], v249 offset:14336
	v_mfma_f32_16x16x32_bf16 v[140:143], v[220:223], v[208:211], v[140:143]
	ds_read_b128 v[182:185], v249 offset:15360
	s_add_u32 m0, s25, s24
	v_mfma_f32_16x16x32_bf16 v[100:103], v[224:227], v[186:189], v[100:103]
	global_load_lds_dwordx4 v156, s[26:27]
	v_mfma_f32_16x16x32_bf16 v[52:55], v[224:227], v[190:193], v[52:55]
	v_mfma_f32_16x16x32_bf16 v[124:127], v[224:227], v[194:197], v[124:127]
	s_add_u32 m0, m0, 0x1000
	v_mfma_f32_16x16x32_bf16 v[144:147], v[224:227], v[208:211], v[144:147]
	global_load_lds_dwordx4 v157, s[26:27]
	v_mfma_f32_16x16x32_bf16 v[60:63], v[228:231], v[186:189], v[60:63]
	v_mfma_f32_16x16x32_bf16 v[36:39], v[228:231], v[190:193], v[36:39]
	s_add_u32 m0, m0, 0x1000
	v_mfma_f32_16x16x32_bf16 v[80:83], v[228:231], v[194:197], v[80:83]
	global_load_lds_dwordx4 v156, s[28:29]
	v_mfma_f32_16x16x32_bf16 v[92:95], v[228:231], v[208:211], v[92:95]
	v_mfma_f32_16x16x32_bf16 v[48:51], v[232:235], v[186:189], v[48:51]
	s_add_u32 m0, m0, 0x1000
	v_mfma_f32_16x16x32_bf16 v[32:35], v[232:235], v[190:193], v[32:35]
	global_load_lds_dwordx4 v157, s[28:29]
	v_mfma_f32_16x16x32_bf16 v[84:87], v[232:235], v[194:197], v[84:87]
	v_mfma_f32_16x16x32_bf16 v[88:91], v[232:235], v[208:211], v[88:91]
	s_add_u32 m0, m0, 0x1000
	v_mfma_f32_16x16x32_bf16 v[44:47], v[236:239], v[186:189], v[44:47]
	global_load_lds_dwordx4 v158, s[28:29]
	v_mfma_f32_16x16x32_bf16 v[28:31], v[236:239], v[190:193], v[28:31]
	v_mfma_f32_16x16x32_bf16 v[96:99], v[236:239], v[194:197], v[96:99]
	s_add_u32 m0, m0, 0x1000
	v_mfma_f32_16x16x32_bf16 v[76:79], v[236:239], v[208:211], v[76:79]
	global_load_lds_dwordx4 v159, s[28:29]
	v_mfma_f32_16x16x32_bf16 v[40:43], v[240:243], v[186:189], v[40:43]
	v_mfma_f32_16x16x32_bf16 v[24:27], v[240:243], v[190:193], v[24:27]
	v_mfma_f32_16x16x32_bf16 v[72:75], v[240:243], v[194:197], v[72:75]
	v_mfma_f32_16x16x32_bf16 v[148:151], v[240:243], v[208:211], v[148:151]
	s_add_u32 s26, s26, 0x200000
	s_addc_u32 s27, s27, 0
	s_add_u32 s28, s28, 0x10000
	s_addc_u32 s29, s29, 0
	s_add_u32 s25, s25, 24576
	s_cmp_eq_u32 s25, 73728
	s_cselect_b32 s25, 0, s25
	s_add_u32 s30, s30, 24576
	s_cmp_eq_u32 s30, 73728
	s_cselect_b32 s30, 0, s30
	s_waitcnt vmcnt(6)
	s_waitcnt lgkmcnt(0)
	s_barrier
	v_add_u32_e32 v248, s30, v155
	v_add_u32_e32 v249, s30, v160
	v_mfma_f32_16x16x32_bf16 v[128:131], v[16:19], v[0:3], v[128:131]
	ds_read_b128 v[186:189], v248
	v_mfma_f32_16x16x32_bf16 v[68:71], v[16:19], v[4:7], v[68:71]
	ds_read_b128 v[212:215], v249 offset:8192
	v_mfma_f32_16x16x32_bf16 v[108:111], v[16:19], v[8:11], v[108:111]
	ds_read_b128 v[190:193], v248 offset:1024
	v_mfma_f32_16x16x32_bf16 v[132:135], v[16:19], v[12:15], v[132:135]
	ds_read_b128 v[216:219], v249 offset:9216
	v_mfma_f32_16x16x32_bf16 v[120:123], v[20:23], v[0:3], v[120:123]
	ds_read_b128 v[194:197], v248 offset:2048
	v_mfma_f32_16x16x32_bf16 v[64:67], v[20:23], v[4:7], v[64:67]
	ds_read_b128 v[220:223], v249 offset:10240
	v_mfma_f32_16x16x32_bf16 v[112:115], v[20:23], v[8:11], v[112:115]
	ds_read_b128 v[208:211], v248 offset:3072
	v_mfma_f32_16x16x32_bf16 v[136:139], v[20:23], v[12:15], v[136:139]
	ds_read_b128 v[224:227], v249 offset:11264
	v_mfma_f32_16x16x32_bf16 v[104:107], v[162:165], v[0:3], v[104:107]
	ds_read_b128 v[228:231], v249 offset:12288
	v_mfma_f32_16x16x32_bf16 v[56:59], v[162:165], v[4:7], v[56:59]
	ds_read_b128 v[232:235], v249 offset:13312
	v_mfma_f32_16x16x32_bf16 v[116:119], v[162:165], v[8:11], v[116:119]
	ds_read_b128 v[236:239], v249 offset:14336
	v_mfma_f32_16x16x32_bf16 v[140:143], v[162:165], v[12:15], v[140:143]
	ds_read_b128 v[240:243], v249 offset:15360
	v_mfma_f32_16x16x32_bf16 v[100:103], v[166:169], v[0:3], v[100:103]
	v_mfma_f32_16x16x32_bf16 v[52:55], v[166:169], v[4:7], v[52:55]
	v_mfma_f32_16x16x32_bf16 v[124:127], v[166:169], v[8:11], v[124:127]
	v_mfma_f32_16x16x32_bf16 v[144:147], v[166:169], v[12:15], v[144:147]
	v_mfma_f32_16x16x32_bf16 v[60:63], v[170:173], v[0:3], v[60:63]
	v_mfma_f32_16x16x32_bf16 v[36:39], v[170:173], v[4:7], v[36:39]
	v_mfma_f32_16x16x32_bf16 v[80:83], v[170:173], v[8:11], v[80:83]
	v_mfma_f32_16x16x32_bf16 v[92:95], v[170:173], v[12:15], v[92:95]
	v_mfma_f32_16x16x32_bf16 v[48:51], v[174:177], v[0:3], v[48:51]
	v_mfma_f32_16x16x32_bf16 v[32:35], v[174:177], v[4:7], v[32:35]
	v_mfma_f32_16x16x32_bf16 v[84:87], v[174:177], v[8:11], v[84:87]
	v_mfma_f32_16x16x32_bf16 v[88:91], v[174:177], v[12:15], v[88:91]
	v_mfma_f32_16x16x32_bf16 v[44:47], v[178:181], v[0:3], v[44:47]
	v_mfma_f32_16x16x32_bf16 v[28:31], v[178:181], v[4:7], v[28:31]
	v_mfma_f32_16x16x32_bf16 v[96:99], v[178:181], v[8:11], v[96:99]
	v_mfma_f32_16x16x32_bf16 v[76:79], v[178:181], v[12:15], v[76:79]
	v_mfma_f32_16x16x32_bf16 v[40:43], v[182:185], v[0:3], v[40:43]
	v_mfma_f32_16x16x32_bf16 v[24:27], v[182:185], v[4:7], v[24:27]
	v_mfma_f32_16x16x32_bf16 v[72:75], v[182:185], v[8:11], v[72:75]
	v_mfma_f32_16x16x32_bf16 v[148:151], v[182:185], v[12:15], v[148:151]
	s_add_u32 s30, s30, 24576
	s_cmp_eq_u32 s30, 73728
	s_cselect_b32 s30, 0, s30
	s_waitcnt vmcnt(0)
	s_waitcnt lgkmcnt(0)
	s_barrier
	v_add_u32_e32 v248, s30, v155
	v_add_u32_e32 v249, s30, v160
	v_mfma_f32_16x16x32_bf16 v[128:131], v[212:215], v[186:189], v[128:131]
	ds_read_b128 v[0:3], v248
	v_mfma_f32_16x16x32_bf16 v[68:71], v[212:215], v[190:193], v[68:71]
	ds_read_b128 v[16:19], v249 offset:8192
	v_mfma_f32_16x16x32_bf16 v[108:111], v[212:215], v[194:197], v[108:111]
	ds_read_b128 v[4:7], v248 offset:1024
	v_mfma_f32_16x16x32_bf16 v[132:135], v[212:215], v[208:211], v[132:135]
	ds_read_b128 v[20:23], v249 offset:9216
	v_mfma_f32_16x16x32_bf16 v[120:123], v[216:219], v[186:189], v[120:123]
	ds_read_b128 v[8:11], v248 offset:2048
	v_mfma_f32_16x16x32_bf16 v[64:67], v[216:219], v[190:193], v[64:67]
	ds_read_b128 v[162:165], v249 offset:10240
	v_mfma_f32_16x16x32_bf16 v[112:115], v[216:219], v[194:197], v[112:115]
	ds_read_b128 v[12:15], v248 offset:3072
	v_mfma_f32_16x16x32_bf16 v[136:139], v[216:219], v[208:211], v[136:139]
	ds_read_b128 v[166:169], v249 offset:11264
	v_mfma_f32_16x16x32_bf16 v[104:107], v[220:223], v[186:189], v[104:107]
	ds_read_b128 v[170:173], v249 offset:12288
	v_mfma_f32_16x16x32_bf16 v[56:59], v[220:223], v[190:193], v[56:59]
	ds_read_b128 v[174:177], v249 offset:13312
	v_mfma_f32_16x16x32_bf16 v[116:119], v[220:223], v[194:197], v[116:119]
	ds_read_b128 v[178:181], v249 offset:14336
	v_mfma_f32_16x16x32_bf16 v[140:143], v[220:223], v[208:211], v[140:143]
	ds_read_b128 v[182:185], v249 offset:15360
	v_mfma_f32_16x16x32_bf16 v[100:103], v[224:227], v[186:189], v[100:103]
	v_mfma_f32_16x16x32_bf16 v[52:55], v[224:227], v[190:193], v[52:55]
	v_mfma_f32_16x16x32_bf16 v[124:127], v[224:227], v[194:197], v[124:127]
	v_mfma_f32_16x16x32_bf16 v[144:147], v[224:227], v[208:211], v[144:147]
	v_mfma_f32_16x16x32_bf16 v[60:63], v[228:231], v[186:189], v[60:63]
	v_mfma_f32_16x16x32_bf16 v[36:39], v[228:231], v[190:193], v[36:39]
	v_mfma_f32_16x16x32_bf16 v[80:83], v[228:231], v[194:197], v[80:83]
	v_mfma_f32_16x16x32_bf16 v[92:95], v[228:231], v[208:211], v[92:95]
	v_mfma_f32_16x16x32_bf16 v[48:51], v[232:235], v[186:189], v[48:51]
	v_mfma_f32_16x16x32_bf16 v[32:35], v[232:235], v[190:193], v[32:35]
	v_mfma_f32_16x16x32_bf16 v[84:87], v[232:235], v[194:197], v[84:87]
	v_mfma_f32_16x16x32_bf16 v[88:91], v[232:235], v[208:211], v[88:91]
	v_mfma_f32_16x16x32_bf16 v[44:47], v[236:239], v[186:189], v[44:47]
	v_mfma_f32_16x16x32_bf16 v[28:31], v[236:239], v[190:193], v[28:31]
	v_mfma_f32_16x16x32_bf16 v[96:99], v[236:239], v[194:197], v[96:99]
	v_mfma_f32_16x16x32_bf16 v[76:79], v[236:239], v[208:211], v[76:79]
	v_mfma_f32_16x16x32_bf16 v[40:43], v[240:243], v[186:189], v[40:43]
	v_mfma_f32_16x16x32_bf16 v[24:27], v[240:243], v[190:193], v[24:27]
	v_mfma_f32_16x16x32_bf16 v[72:75], v[240:243], v[194:197], v[72:75]
	v_mfma_f32_16x16x32_bf16 v[148:151], v[240:243], v[208:211], v[148:151]
	s_add_u32 s30, s30, 24576
	s_cmp_eq_u32 s30, 73728
	s_cselect_b32 s30, 0, s30
	s_waitcnt lgkmcnt(0)
	s_barrier
	v_mfma_f32_16x16x32_bf16 v[128:131], v[16:19], v[0:3], v[128:131]
	v_mfma_f32_16x16x32_bf16 v[68:71], v[16:19], v[4:7], v[68:71]
	v_mfma_f32_16x16x32_bf16 v[108:111], v[16:19], v[8:11], v[108:111]
	v_mfma_f32_16x16x32_bf16 v[132:135], v[16:19], v[12:15], v[132:135]
	v_mfma_f32_16x16x32_bf16 v[120:123], v[20:23], v[0:3], v[120:123]
	v_mfma_f32_16x16x32_bf16 v[64:67], v[20:23], v[4:7], v[64:67]
	v_mfma_f32_16x16x32_bf16 v[112:115], v[20:23], v[8:11], v[112:115]
	v_mfma_f32_16x16x32_bf16 v[136:139], v[20:23], v[12:15], v[136:139]
	v_mfma_f32_16x16x32_bf16 v[104:107], v[162:165], v[0:3], v[104:107]
	v_mfma_f32_16x16x32_bf16 v[56:59], v[162:165], v[4:7], v[56:59]
	v_mfma_f32_16x16x32_bf16 v[116:119], v[162:165], v[8:11], v[116:119]
	v_mfma_f32_16x16x32_bf16 v[140:143], v[162:165], v[12:15], v[140:143]
	v_mfma_f32_16x16x32_bf16 v[100:103], v[166:169], v[0:3], v[100:103]
	v_mfma_f32_16x16x32_bf16 v[52:55], v[166:169], v[4:7], v[52:55]
	v_mfma_f32_16x16x32_bf16 v[124:127], v[166:169], v[8:11], v[124:127]
	v_mfma_f32_16x16x32_bf16 v[144:147], v[166:169], v[12:15], v[144:147]
	v_mfma_f32_16x16x32_bf16 v[60:63], v[170:173], v[0:3], v[60:63]
	v_mfma_f32_16x16x32_bf16 v[36:39], v[170:173], v[4:7], v[36:39]
	v_mfma_f32_16x16x32_bf16 v[80:83], v[170:173], v[8:11], v[80:83]
	v_mfma_f32_16x16x32_bf16 v[92:95], v[170:173], v[12:15], v[92:95]
	v_mfma_f32_16x16x32_bf16 v[48:51], v[174:177], v[0:3], v[48:51]
	v_mfma_f32_16x16x32_bf16 v[32:35], v[174:177], v[4:7], v[32:35]
	v_mfma_f32_16x16x32_bf16 v[84:87], v[174:177], v[8:11], v[84:87]
	v_mfma_f32_16x16x32_bf16 v[88:91], v[174:177], v[12:15], v[88:91]
	v_mfma_f32_16x16x32_bf16 v[44:47], v[178:181], v[0:3], v[44:47]
	v_mfma_f32_16x16x32_bf16 v[28:31], v[178:181], v[4:7], v[28:31]
	v_mfma_f32_16x16x32_bf16 v[96:99], v[178:181], v[8:11], v[96:99]
	v_mfma_f32_16x16x32_bf16 v[76:79], v[178:181], v[12:15], v[76:79]
	v_mfma_f32_16x16x32_bf16 v[40:43], v[182:185], v[0:3], v[40:43]
	v_mfma_f32_16x16x32_bf16 v[24:27], v[182:185], v[4:7], v[24:27]
	v_mfma_f32_16x16x32_bf16 v[72:75], v[182:185], v[8:11], v[72:75]
	v_mfma_f32_16x16x32_bf16 v[148:151], v[182:185], v[12:15], v[148:151]
	v_mov_b32 v250, v198
	s_nop 0
	v_and_b32_e32 v251, 15, v250
	v_bfe_u32 v156, v250, 4, 2
	v_bfe_u32 v157, v250, 6, 1
	v_bfe_u32 v158, v250, 7, 1
	v_lshl_add_u32 v158, v158, 6, s4
	v_add_u32_e32 v158, v158, v251
	v_lshl_add_u32 v157, v157, 7, s5
	v_lshl_add_u32 v159, v156, 2, v157
	v_lshlrev_b32_e32 v246, 2, v159
	v_lshl_add_u32 v244, v158, 12, v246
	v_lshlrev_b32_e32 v161, 1, v159
	v_lshl_add_u32 v245, v158, 11, v161
	v_and_b32_e32 v254, 1, v156
	v_mul_u32_u24_e32 v254, 24, v254
	v_lshl_add_u32 v254, v156, 3, v254
	v_lshl_add_u32 v254, v158, 6, v254
	v_lshrrev_b32_e32 v161, 5, v157
	v_lshl_add_u32 v254, v161, 21, v254
	v_lshrrev_b32_e32 v161, 6, v157
	v_lshlrev_b32_e32 v161, 2, v161
	v_lshl_add_u32 v247, v158, 6, v161
	v_xor_b32_e32 v248, 16, v200
	v_lshlrev_b32_e32 v248, 2, v248
	v_xor_b32_e32 v249, 32, v200
	v_lshlrev_b32_e32 v249, 2, v249
	s_mov_b32 s24, s78
	s_mov_b32 s25, s79
	s_mov_b32 s26, s78
	s_mov_b32 s27, s79
	s_mov_b32 s28, s96
	s_mov_b32 s29, s97
	s_mov_b32 s30, s94
	s_mov_b32 s31, s95
	s_mov_b32 s22, s28
	s_mov_b32 s23, s29
	s_cmp_lg_u64 s[8:9], 0
	s_cbranch_scc0 .Lgm2_noemit
	global_load_dwordx4 v[208:211], v246, s[10:11]
	global_load_dwordx4 v[212:215], v246, s[10:11] offset:64
	global_load_dwordx4 v[216:219], v246, s[10:11] offset:128
	global_load_dwordx4 v[220:223], v246, s[10:11] offset:192
	global_load_dwordx4 v[224:227], v246, s[10:11] offset:256
	global_load_dwordx4 v[228:231], v246, s[10:11] offset:320
	global_load_dwordx4 v[232:235], v246, s[10:11] offset:384
	global_load_dwordx4 v[236:239], v246, s[10:11] offset:448
	global_load_dwordx4 v[0:3], v244, s[24:25]
	global_load_dwordx4 v[4:7], v244, s[24:25] offset:64
	global_load_dwordx4 v[8:11], v244, s[24:25] offset:128
	global_load_dwordx4 v[12:15], v244, s[24:25] offset:192
	global_load_dwordx4 v[16:19], v244, s[24:25] offset:256
	global_load_dwordx4 v[20:23], v244, s[24:25] offset:320
	global_load_dwordx4 v[162:165], v244, s[24:25] offset:384
	global_load_dwordx4 v[166:169], v244, s[24:25] offset:448
	s_add_u32 s24, s24, 0x10000
	s_addc_u32 s25, s25, 0
	global_load_dwordx4 v[170:173], v244, s[24:25]
	global_load_dwordx4 v[174:177], v244, s[24:25] offset:64
	global_load_dwordx4 v[178:181], v244, s[24:25] offset:128
	global_load_dwordx4 v[182:185], v244, s[24:25] offset:192
	global_load_dwordx4 v[186:189], v244, s[24:25] offset:256
	global_load_dwordx4 v[190:193], v244, s[24:25] offset:320
	global_load_dwordx4 v[194:197], v244, s[24:25] offset:384
	global_load_dwordx4 v[240:243], v244, s[24:25] offset:448
	s_add_u32 s24, s24, 0x10000
	s_addc_u32 s25, s25, 0
	s_waitcnt vmcnt(12)
	v_add_f32_e32 v0, v128, v0
	v_add_f32_e32 v1, v129, v1
	v_add_f32_e32 v2, v130, v2
	v_add_f32_e32 v3, v131, v3
	global_store_dwordx4 v244, v[0:3], s[26:27]
	v_mul_f32_e32 v158, v0, v0
	v_mul_f32_e32 v159, v1, v1
	v_mul_f32_e32 v250, v2, v2
	v_mul_f32_e32 v251, v3, v3
	v_add_f32_e32 v158, v158, v159
	v_add_f32_e32 v250, v250, v251
	v_add_f32_e32 v161, v158, v250
	v_mul_f32_e32 v156, v0, v208
	v_mul_f32_e32 v157, v1, v209
	v_mul_f32_e32 v158, v2, v210
	v_mul_f32_e32 v159, v3, v211
	v_cvt_pk_bf16_f32 v156, v156, v157
	v_cvt_pk_bf16_f32 v157, v158, v159
	v_add_f32_e32 v4, v120, v4
	v_add_f32_e32 v5, v121, v5
	v_add_f32_e32 v6, v122, v6
	v_add_f32_e32 v7, v123, v7
	global_store_dwordx4 v244, v[4:7], s[26:27] offset:64
	v_mul_f32_e32 v158, v4, v4
	v_mul_f32_e32 v159, v5, v5
	v_mul_f32_e32 v250, v6, v6
	v_mul_f32_e32 v251, v7, v7
	v_add_f32_e32 v158, v158, v159
	v_add_f32_e32 v250, v250, v251
	v_add_f32_e32 v158, v158, v250
	v_add_f32_e32 v161, v161, v158
	v_mul_f32_e32 v158, v4, v212
	v_mul_f32_e32 v159, v5, v213
	v_mul_f32_e32 v250, v6, v214
	v_mul_f32_e32 v251, v7, v215
	v_cvt_pk_bf16_f32 v158, v158, v159
	v_cvt_pk_bf16_f32 v159, v250, v251
	s_nop 1
	v_permlane16_swap_b32_e32 v156, v158
	v_permlane16_swap_b32_e32 v157, v159
	s_add_u32 s28, s22, 0x0
	s_addc_u32 s29, s23, 0
	global_store_dwordx4 v254, v[156:159], s[28:29]
	v_add_f32_e32 v8, v104, v8
	v_add_f32_e32 v9, v105, v9
	v_add_f32_e32 v10, v106, v10
	v_add_f32_e32 v11, v107, v11
	global_store_dwordx4 v244, v[8:11], s[26:27] offset:128
	v_mul_f32_e32 v158, v8, v8
	v_mul_f32_e32 v159, v9, v9
	v_mul_f32_e32 v250, v10, v10
	v_mul_f32_e32 v251, v11, v11
	v_add_f32_e32 v158, v158, v159
	v_add_f32_e32 v250, v250, v251
	v_add_f32_e32 v158, v158, v250
	v_add_f32_e32 v161, v161, v158
	v_mul_f32_e32 v156, v8, v216
	v_mul_f32_e32 v157, v9, v217
	v_mul_f32_e32 v158, v10, v218
	v_mul_f32_e32 v159, v11, v219
	v_cvt_pk_bf16_f32 v156, v156, v157
	v_cvt_pk_bf16_f32 v157, v158, v159
	v_add_f32_e32 v12, v100, v12
	v_add_f32_e32 v13, v101, v13
	v_add_f32_e32 v14, v102, v14
	v_add_f32_e32 v15, v103, v15
	global_store_dwordx4 v244, v[12:15], s[26:27] offset:192
	v_mul_f32_e32 v158, v12, v12
	v_mul_f32_e32 v159, v13, v13
	v_mul_f32_e32 v250, v14, v14
	v_mul_f32_e32 v251, v15, v15
	v_add_f32_e32 v158, v158, v159
	v_add_f32_e32 v250, v250, v251
	v_add_f32_e32 v158, v158, v250
	v_add_f32_e32 v161, v161, v158
	v_mul_f32_e32 v158, v12, v220
	v_mul_f32_e32 v159, v13, v221
	v_mul_f32_e32 v250, v14, v222
	v_mul_f32_e32 v251, v15, v223
	v_cvt_pk_bf16_f32 v158, v158, v159
	v_cvt_pk_bf16_f32 v159, v250, v251
	s_nop 1
	v_permlane16_swap_b32_e32 v156, v158
	v_permlane16_swap_b32_e32 v157, v159
	s_add_u32 s28, s22, 0x200000
	s_addc_u32 s29, s23, 0
	global_store_dwordx4 v254, v[156:159], s[28:29]
	ds_bpermute_b32 v158, v248, v161
	s_waitcnt lgkmcnt(0)
	v_add_f32_e32 v161, v161, v158
	ds_bpermute_b32 v158, v249, v161
	s_waitcnt lgkmcnt(0)
	v_add_f32_e32 v161, v161, v158
	global_store_dword v247, v161, s[30:31]
	global_load_dwordx4 v[0:3], v244, s[24:25]
	global_load_dwordx4 v[4:7], v244, s[24:25] offset:64
	global_load_dwordx4 v[8:11], v244, s[24:25] offset:128
	global_load_dwordx4 v[12:15], v244, s[24:25] offset:192
	s_waitcnt vmcnt(19)
	v_add_f32_e32 v16, v60, v16
	v_add_f32_e32 v17, v61, v17
	v_add_f32_e32 v18, v62, v18
	v_add_f32_e32 v19, v63, v19
	global_store_dwordx4 v244, v[16:19], s[26:27] offset:256
	v_mul_f32_e32 v158, v16, v16
	v_mul_f32_e32 v159, v17, v17
	v_mul_f32_e32 v250, v18, v18
	v_mul_f32_e32 v251, v19, v19
	v_add_f32_e32 v158, v158, v159
	v_add_f32_e32 v250, v250, v251
	v_add_f32_e32 v161, v158, v250
	v_mul_f32_e32 v156, v16, v224
	v_mul_f32_e32 v157, v17, v225
	v_mul_f32_e32 v158, v18, v226
	v_mul_f32_e32 v159, v19, v227
	v_cvt_pk_bf16_f32 v156, v156, v157
	v_cvt_pk_bf16_f32 v157, v158, v159
	v_add_f32_e32 v20, v48, v20
	v_add_f32_e32 v21, v49, v21
	v_add_f32_e32 v22, v50, v22
	v_add_f32_e32 v23, v51, v23
	global_store_dwordx4 v244, v[20:23], s[26:27] offset:320
	v_mul_f32_e32 v158, v20, v20
	v_mul_f32_e32 v159, v21, v21
	v_mul_f32_e32 v250, v22, v22
	v_mul_f32_e32 v251, v23, v23
	v_add_f32_e32 v158, v158, v159
	v_add_f32_e32 v250, v250, v251
	v_add_f32_e32 v158, v158, v250
	v_add_f32_e32 v161, v161, v158
	v_mul_f32_e32 v158, v20, v228
	v_mul_f32_e32 v159, v21, v229
	v_mul_f32_e32 v250, v22, v230
	v_mul_f32_e32 v251, v23, v231
	v_cvt_pk_bf16_f32 v158, v158, v159
	v_cvt_pk_bf16_f32 v159, v250, v251
	s_nop 1
	v_permlane16_swap_b32_e32 v156, v158
	v_permlane16_swap_b32_e32 v157, v159
	s_add_u32 s28, s22, 0x400000
	s_addc_u32 s29, s23, 0
	global_store_dwordx4 v254, v[156:159], s[28:29]
	v_add_f32_e32 v162, v44, v162
	v_add_f32_e32 v163, v45, v163
	v_add_f32_e32 v164, v46, v164
	v_add_f32_e32 v165, v47, v165
	global_store_dwordx4 v244, v[162:165], s[26:27] offset:384
	v_mul_f32_e32 v158, v162, v162
	v_mul_f32_e32 v159, v163, v163
	v_mul_f32_e32 v250, v164, v164
	v_mul_f32_e32 v251, v165, v165
	v_add_f32_e32 v158, v158, v159
	v_add_f32_e32 v250, v250, v251
	v_add_f32_e32 v158, v158, v250
	v_add_f32_e32 v161, v161, v158
	v_mul_f32_e32 v156, v162, v232
	v_mul_f32_e32 v157, v163, v233
	v_mul_f32_e32 v158, v164, v234
	v_mul_f32_e32 v159, v165, v235
	v_cvt_pk_bf16_f32 v156, v156, v157
	v_cvt_pk_bf16_f32 v157, v158, v159
	v_add_f32_e32 v166, v40, v166
	v_add_f32_e32 v167, v41, v167
	v_add_f32_e32 v168, v42, v168
	v_add_f32_e32 v169, v43, v169
	global_store_dwordx4 v244, v[166:169], s[26:27] offset:448
	v_mul_f32_e32 v158, v166, v166
	v_mul_f32_e32 v159, v167, v167
	v_mul_f32_e32 v250, v168, v168
	v_mul_f32_e32 v251, v169, v169
	v_add_f32_e32 v158, v158, v159
	v_add_f32_e32 v250, v250, v251
	v_add_f32_e32 v158, v158, v250
	v_add_f32_e32 v161, v161, v158
	v_mul_f32_e32 v158, v166, v236
	v_mul_f32_e32 v159, v167, v237
	v_mul_f32_e32 v250, v168, v238
	v_mul_f32_e32 v251, v169, v239
	v_cvt_pk_bf16_f32 v158, v158, v159
	v_cvt_pk_bf16_f32 v159, v250, v251
	s_nop 1
	v_permlane16_swap_b32_e32 v156, v158
	v_permlane16_swap_b32_e32 v157, v159
	s_add_u32 s28, s22, 0x600000
	s_addc_u32 s29, s23, 0
	global_store_dwordx4 v254, v[156:159], s[28:29]
	ds_bpermute_b32 v158, v248, v161
	s_waitcnt lgkmcnt(0)
	v_add_f32_e32 v161, v161, v158
	ds_bpermute_b32 v158, v249, v161
	s_waitcnt lgkmcnt(0)
	v_add_f32_e32 v161, v161, v158
	global_store_dword v247, v161, s[30:31] offset:4
	s_add_u32 s26, s26, 0x10000
	s_addc_u32 s27, s27, 0
	s_add_u32 s30, s30, 0x400
	s_addc_u32 s31, s31, 0
	global_load_dwordx4 v[16:19], v244, s[24:25] offset:256
	global_load_dwordx4 v[20:23], v244, s[24:25] offset:320
	global_load_dwordx4 v[162:165], v244, s[24:25] offset:384
	global_load_dwordx4 v[166:169], v244, s[24:25] offset:448
	s_add_u32 s24, s24, 0x10000
	s_addc_u32 s25, s25, 0
	s_waitcnt vmcnt(26)
	v_add_f32_e32 v170, v68, v170
	v_add_f32_e32 v171, v69, v171
	v_add_f32_e32 v172, v70, v172
	v_add_f32_e32 v173, v71, v173
	global_store_dwordx4 v244, v[170:173], s[26:27]
	v_mul_f32_e32 v158, v170, v170
	v_mul_f32_e32 v159, v171, v171
	v_mul_f32_e32 v250, v172, v172
	v_mul_f32_e32 v251, v173, v173
	v_add_f32_e32 v158, v158, v159
	v_add_f32_e32 v250, v250, v251
	v_add_f32_e32 v161, v158, v250
	v_mul_f32_e32 v156, v170, v208
	v_mul_f32_e32 v157, v171, v209
	v_mul_f32_e32 v158, v172, v210
	v_mul_f32_e32 v159, v173, v211
	v_cvt_pk_bf16_f32 v156, v156, v157
	v_cvt_pk_bf16_f32 v157, v158, v159
	v_add_f32_e32 v174, v64, v174
	v_add_f32_e32 v175, v65, v175
	v_add_f32_e32 v176, v66, v176
	v_add_f32_e32 v177, v67, v177
	global_store_dwordx4 v244, v[174:177], s[26:27] offset:64
	v_mul_f32_e32 v158, v174, v174
	v_mul_f32_e32 v159, v175, v175
	v_mul_f32_e32 v250, v176, v176
	v_mul_f32_e32 v251, v177, v177
	v_add_f32_e32 v158, v158, v159
	v_add_f32_e32 v250, v250, v251
	v_add_f32_e32 v158, v158, v250
	v_add_f32_e32 v161, v161, v158
	v_mul_f32_e32 v158, v174, v212
	v_mul_f32_e32 v159, v175, v213
	v_mul_f32_e32 v250, v176, v214
	v_mul_f32_e32 v251, v177, v215
	v_cvt_pk_bf16_f32 v158, v158, v159
	v_cvt_pk_bf16_f32 v159, v250, v251
	s_nop 1
	v_permlane16_swap_b32_e32 v156, v158
	v_permlane16_swap_b32_e32 v157, v159
	s_add_u32 s28, s22, 0x400
	s_addc_u32 s29, s23, 0
	global_store_dwordx4 v254, v[156:159], s[28:29]
	v_add_f32_e32 v178, v56, v178
	v_add_f32_e32 v179, v57, v179
	v_add_f32_e32 v180, v58, v180
	v_add_f32_e32 v181, v59, v181
	global_store_dwordx4 v244, v[178:181], s[26:27] offset:128
	v_mul_f32_e32 v158, v178, v178
	v_mul_f32_e32 v159, v179, v179
	v_mul_f32_e32 v250, v180, v180
	v_mul_f32_e32 v251, v181, v181
	v_add_f32_e32 v158, v158, v159
	v_add_f32_e32 v250, v250, v251
	v_add_f32_e32 v158, v158, v250
	v_add_f32_e32 v161, v161, v158
	v_mul_f32_e32 v156, v178, v216
	v_mul_f32_e32 v157, v179, v217
	v_mul_f32_e32 v158, v180, v218
	v_mul_f32_e32 v159, v181, v219
	v_cvt_pk_bf16_f32 v156, v156, v157
	v_cvt_pk_bf16_f32 v157, v158, v159
	v_add_f32_e32 v182, v52, v182
	v_add_f32_e32 v183, v53, v183
	v_add_f32_e32 v184, v54, v184
	v_add_f32_e32 v185, v55, v185
	global_store_dwordx4 v244, v[182:185], s[26:27] offset:192
	v_mul_f32_e32 v158, v182, v182
	v_mul_f32_e32 v159, v183, v183
	v_mul_f32_e32 v250, v184, v184
	v_mul_f32_e32 v251, v185, v185
	v_add_f32_e32 v158, v158, v159
	v_add_f32_e32 v250, v250, v251
	v_add_f32_e32 v158, v158, v250
	v_add_f32_e32 v161, v161, v158
	v_mul_f32_e32 v158, v182, v220
	v_mul_f32_e32 v159, v183, v221
	v_mul_f32_e32 v250, v184, v222
	v_mul_f32_e32 v251, v185, v223
	v_cvt_pk_bf16_f32 v158, v158, v159
	v_cvt_pk_bf16_f32 v159, v250, v251
	s_nop 1
	v_permlane16_swap_b32_e32 v156, v158
	v_permlane16_swap_b32_e32 v157, v159
	s_add_u32 s28, s22, 0x200400
	s_addc_u32 s29, s23, 0
	global_store_dwordx4 v254, v[156:159], s[28:29]
	ds_bpermute_b32 v158, v248, v161
	s_waitcnt lgkmcnt(0)
	v_add_f32_e32 v161, v161, v158
	ds_bpermute_b32 v158, v249, v161
	s_waitcnt lgkmcnt(0)
	v_add_f32_e32 v161, v161, v158
	global_store_dword v247, v161, s[30:31]
	global_load_dwordx4 v[170:173], v244, s[24:25]
	global_load_dwordx4 v[174:177], v244, s[24:25] offset:64
	global_load_dwordx4 v[178:181], v244, s[24:25] offset:128
	global_load_dwordx4 v[182:185], v244, s[24:25] offset:192
	s_waitcnt vmcnt(33)
	v_add_f32_e32 v186, v36, v186
	v_add_f32_e32 v187, v37, v187
	v_add_f32_e32 v188, v38, v188
	v_add_f32_e32 v189, v39, v189
	global_store_dwordx4 v244, v[186:189], s[26:27] offset:256
	v_mul_f32_e32 v158, v186, v186
	v_mul_f32_e32 v159, v187, v187
	v_mul_f32_e32 v250, v188, v188
	v_mul_f32_e32 v251, v189, v189
	v_add_f32_e32 v158, v158, v159
	v_add_f32_e32 v250, v250, v251
	v_add_f32_e32 v161, v158, v250
	v_mul_f32_e32 v156, v186, v224
	v_mul_f32_e32 v157, v187, v225
	v_mul_f32_e32 v158, v188, v226
	v_mul_f32_e32 v159, v189, v227
	v_cvt_pk_bf16_f32 v156, v156, v157
	v_cvt_pk_bf16_f32 v157, v158, v159
	v_add_f32_e32 v190, v32, v190
	v_add_f32_e32 v191, v33, v191
	v_add_f32_e32 v192, v34, v192
	v_add_f32_e32 v193, v35, v193
	global_store_dwordx4 v244, v[190:193], s[26:27] offset:320
	v_mul_f32_e32 v158, v190, v190
	v_mul_f32_e32 v159, v191, v191
	v_mul_f32_e32 v250, v192, v192
	v_mul_f32_e32 v251, v193, v193
	v_add_f32_e32 v158, v158, v159
	v_add_f32_e32 v250, v250, v251
	v_add_f32_e32 v158, v158, v250
	v_add_f32_e32 v161, v161, v158
	v_mul_f32_e32 v158, v190, v228
	v_mul_f32_e32 v159, v191, v229
	v_mul_f32_e32 v250, v192, v230
	v_mul_f32_e32 v251, v193, v231
	v_cvt_pk_bf16_f32 v158, v158, v159
	v_cvt_pk_bf16_f32 v159, v250, v251
	s_nop 1
	v_permlane16_swap_b32_e32 v156, v158
	v_permlane16_swap_b32_e32 v157, v159
	s_add_u32 s28, s22, 0x400400
	s_addc_u32 s29, s23, 0
	global_store_dwordx4 v254, v[156:159], s[28:29]
	v_add_f32_e32 v194, v28, v194
	v_add_f32_e32 v195, v29, v195
	v_add_f32_e32 v196, v30, v196
	v_add_f32_e32 v197, v31, v197
	global_store_dwordx4 v244, v[194:197], s[26:27] offset:384
	v_mul_f32_e32 v158, v194, v194
	v_mul_f32_e32 v159, v195, v195
	v_mul_f32_e32 v250, v196, v196
	v_mul_f32_e32 v251, v197, v197
	v_add_f32_e32 v158, v158, v159
	v_add_f32_e32 v250, v250, v251
	v_add_f32_e32 v158, v158, v250
	v_add_f32_e32 v161, v161, v158
	v_mul_f32_e32 v156, v194, v232
	v_mul_f32_e32 v157, v195, v233
	v_mul_f32_e32 v158, v196, v234
	v_mul_f32_e32 v159, v197, v235
	v_cvt_pk_bf16_f32 v156, v156, v157
	v_cvt_pk_bf16_f32 v157, v158, v159
	v_add_f32_e32 v240, v24, v240
	v_add_f32_e32 v241, v25, v241
	v_add_f32_e32 v242, v26, v242
	v_add_f32_e32 v243, v27, v243
	global_store_dwordx4 v244, v[240:243], s[26:27] offset:448
	v_mul_f32_e32 v158, v240, v240
	v_mul_f32_e32 v159, v241, v241
	v_mul_f32_e32 v250, v242, v242
	v_mul_f32_e32 v251, v243, v243
	v_add_f32_e32 v158, v158, v159
	v_add_f32_e32 v250, v250, v251
	v_add_f32_e32 v158, v158, v250
	v_add_f32_e32 v161, v161, v158
	v_mul_f32_e32 v158, v240, v236
	v_mul_f32_e32 v159, v241, v237
	v_mul_f32_e32 v250, v242, v238
	v_mul_f32_e32 v251, v243, v239
	v_cvt_pk_bf16_f32 v158, v158, v159
	v_cvt_pk_bf16_f32 v159, v250, v251
	s_nop 1
	v_permlane16_swap_b32_e32 v156, v158
	v_permlane16_swap_b32_e32 v157, v159
	s_add_u32 s28, s22, 0x600400
	s_addc_u32 s29, s23, 0
	global_store_dwordx4 v254, v[156:159], s[28:29]
	ds_bpermute_b32 v158, v248, v161
	s_waitcnt lgkmcnt(0)
	v_add_f32_e32 v161, v161, v158
	ds_bpermute_b32 v158, v249, v161
	s_waitcnt lgkmcnt(0)
	v_add_f32_e32 v161, v161, v158
	global_store_dword v247, v161, s[30:31] offset:4
	s_add_u32 s26, s26, 0x10000
	s_addc_u32 s27, s27, 0
	s_add_u32 s30, s30, 0x400
	s_addc_u32 s31, s31, 0
	global_load_dwordx4 v[186:189], v244, s[24:25] offset:256
	global_load_dwordx4 v[190:193], v244, s[24:25] offset:320
	global_load_dwordx4 v[194:197], v244, s[24:25] offset:384
	global_load_dwordx4 v[240:243], v244, s[24:25] offset:448
	s_add_u32 s24, s24, 0x10000
	s_addc_u32 s25, s25, 0
	s_waitcnt vmcnt(33)
	v_add_f32_e32 v0, v108, v0
	v_add_f32_e32 v1, v109, v1
	v_add_f32_e32 v2, v110, v2
	v_add_f32_e32 v3, v111, v3
	global_store_dwordx4 v244, v[0:3], s[26:27]
	v_mul_f32_e32 v158, v0, v0
	v_mul_f32_e32 v159, v1, v1
	v_mul_f32_e32 v250, v2, v2
	v_mul_f32_e32 v251, v3, v3
	v_add_f32_e32 v158, v158, v159
	v_add_f32_e32 v250, v250, v251
	v_add_f32_e32 v161, v158, v250
	v_mul_f32_e32 v156, v0, v208
	v_mul_f32_e32 v157, v1, v209
	v_mul_f32_e32 v158, v2, v210
	v_mul_f32_e32 v159, v3, v211
	v_cvt_pk_bf16_f32 v156, v156, v157
	v_cvt_pk_bf16_f32 v157, v158, v159
	v_add_f32_e32 v4, v112, v4
	v_add_f32_e32 v5, v113, v5
	v_add_f32_e32 v6, v114, v6
	v_add_f32_e32 v7, v115, v7
	global_store_dwordx4 v244, v[4:7], s[26:27] offset:64
	v_mul_f32_e32 v158, v4, v4
	v_mul_f32_e32 v159, v5, v5
	v_mul_f32_e32 v250, v6, v6
	v_mul_f32_e32 v251, v7, v7
	v_add_f32_e32 v158, v158, v159
	v_add_f32_e32 v250, v250, v251
	v_add_f32_e32 v158, v158, v250
	v_add_f32_e32 v161, v161, v158
	v_mul_f32_e32 v158, v4, v212
	v_mul_f32_e32 v159, v5, v213
	v_mul_f32_e32 v250, v6, v214
	v_mul_f32_e32 v251, v7, v215
	v_cvt_pk_bf16_f32 v158, v158, v159
	v_cvt_pk_bf16_f32 v159, v250, v251
	s_nop 1
	v_permlane16_swap_b32_e32 v156, v158
	v_permlane16_swap_b32_e32 v157, v159
	s_add_u32 s28, s22, 0x800
	s_addc_u32 s29, s23, 0
	global_store_dwordx4 v254, v[156:159], s[28:29]
	v_add_f32_e32 v8, v116, v8
	v_add_f32_e32 v9, v117, v9
	v_add_f32_e32 v10, v118, v10
	v_add_f32_e32 v11, v119, v11
	global_store_dwordx4 v244, v[8:11], s[26:27] offset:128
	v_mul_f32_e32 v158, v8, v8
	v_mul_f32_e32 v159, v9, v9
	v_mul_f32_e32 v250, v10, v10
	v_mul_f32_e32 v251, v11, v11
	v_add_f32_e32 v158, v158, v159
	v_add_f32_e32 v250, v250, v251
	v_add_f32_e32 v158, v158, v250
	v_add_f32_e32 v161, v161, v158
	v_mul_f32_e32 v156, v8, v216
	v_mul_f32_e32 v157, v9, v217
	v_mul_f32_e32 v158, v10, v218
	v_mul_f32_e32 v159, v11, v219
	v_cvt_pk_bf16_f32 v156, v156, v157
	v_cvt_pk_bf16_f32 v157, v158, v159
	v_add_f32_e32 v12, v124, v12
	v_add_f32_e32 v13, v125, v13
	v_add_f32_e32 v14, v126, v14
	v_add_f32_e32 v15, v127, v15
	global_store_dwordx4 v244, v[12:15], s[26:27] offset:192
	v_mul_f32_e32 v158, v12, v12
	v_mul_f32_e32 v159, v13, v13
	v_mul_f32_e32 v250, v14, v14
	v_mul_f32_e32 v251, v15, v15
	v_add_f32_e32 v158, v158, v159
	v_add_f32_e32 v250, v250, v251
	v_add_f32_e32 v158, v158, v250
	v_add_f32_e32 v161, v161, v158
	v_mul_f32_e32 v158, v12, v220
	v_mul_f32_e32 v159, v13, v221
	v_mul_f32_e32 v250, v14, v222
	v_mul_f32_e32 v251, v15, v223
	v_cvt_pk_bf16_f32 v158, v158, v159
	v_cvt_pk_bf16_f32 v159, v250, v251
	s_nop 1
	v_permlane16_swap_b32_e32 v156, v158
	v_permlane16_swap_b32_e32 v157, v159
	s_add_u32 s28, s22, 0x200800
	s_addc_u32 s29, s23, 0
	global_store_dwordx4 v254, v[156:159], s[28:29]
	ds_bpermute_b32 v158, v248, v161
	s_waitcnt lgkmcnt(0)
	v_add_f32_e32 v161, v161, v158
	ds_bpermute_b32 v158, v249, v161
	s_waitcnt lgkmcnt(0)
	v_add_f32_e32 v161, v161, v158
	global_store_dword v247, v161, s[30:31]
	s_waitcnt vmcnt(29)
	v_add_f32_e32 v16, v80, v16
	v_add_f32_e32 v17, v81, v17
	v_add_f32_e32 v18, v82, v18
	v_add_f32_e32 v19, v83, v19
	global_store_dwordx4 v244, v[16:19], s[26:27] offset:256
	v_mul_f32_e32 v158, v16, v16
	v_mul_f32_e32 v159, v17, v17
	v_mul_f32_e32 v250, v18, v18
	v_mul_f32_e32 v251, v19, v19
	v_add_f32_e32 v158, v158, v159
	v_add_f32_e32 v250, v250, v251
	v_add_f32_e32 v161, v158, v250
	v_mul_f32_e32 v156, v16, v224
	v_mul_f32_e32 v157, v17, v225
	v_mul_f32_e32 v158, v18, v226
	v_mul_f32_e32 v159, v19, v227
	v_cvt_pk_bf16_f32 v156, v156, v157
	v_cvt_pk_bf16_f32 v157, v158, v159
	v_add_f32_e32 v20, v84, v20
	v_add_f32_e32 v21, v85, v21
	v_add_f32_e32 v22, v86, v22
	v_add_f32_e32 v23, v87, v23
	global_store_dwordx4 v244, v[20:23], s[26:27] offset:320
	v_mul_f32_e32 v158, v20, v20
	v_mul_f32_e32 v159, v21, v21
	v_mul_f32_e32 v250, v22, v22
	v_mul_f32_e32 v251, v23, v23
	v_add_f32_e32 v158, v158, v159
	v_add_f32_e32 v250, v250, v251
	v_add_f32_e32 v158, v158, v250
	v_add_f32_e32 v161, v161, v158
	v_mul_f32_e32 v158, v20, v228
	v_mul_f32_e32 v159, v21, v229
	v_mul_f32_e32 v250, v22, v230
	v_mul_f32_e32 v251, v23, v231
	v_cvt_pk_bf16_f32 v158, v158, v159
	v_cvt_pk_bf16_f32 v159, v250, v251
	s_nop 1
	v_permlane16_swap_b32_e32 v156, v158
	v_permlane16_swap_b32_e32 v157, v159
	s_add_u32 s28, s22, 0x400800
	s_addc_u32 s29, s23, 0
	global_store_dwordx4 v254, v[156:159], s[28:29]
	v_add_f32_e32 v162, v96, v162
	v_add_f32_e32 v163, v97, v163
	v_add_f32_e32 v164, v98, v164
	v_add_f32_e32 v165, v99, v165
	global_store_dwordx4 v244, v[162:165], s[26:27] offset:384
	v_mul_f32_e32 v158, v162, v162
	v_mul_f32_e32 v159, v163, v163
	v_mul_f32_e32 v250, v164, v164
	v_mul_f32_e32 v251, v165, v165
	v_add_f32_e32 v158, v158, v159
	v_add_f32_e32 v250, v250, v251
	v_add_f32_e32 v158, v158, v250
	v_add_f32_e32 v161, v161, v158
	v_mul_f32_e32 v156, v162, v232
	v_mul_f32_e32 v157, v163, v233
	v_mul_f32_e32 v158, v164, v234
	v_mul_f32_e32 v159, v165, v235
	v_cvt_pk_bf16_f32 v156, v156, v157
	v_cvt_pk_bf16_f32 v157, v158, v159
	v_add_f32_e32 v166, v72, v166
	v_add_f32_e32 v167, v73, v167
	v_add_f32_e32 v168, v74, v168
	v_add_f32_e32 v169, v75, v169
	global_store_dwordx4 v244, v[166:169], s[26:27] offset:448
	v_mul_f32_e32 v158, v166, v166
	v_mul_f32_e32 v159, v167, v167
	v_mul_f32_e32 v250, v168, v168
	v_mul_f32_e32 v251, v169, v169
	v_add_f32_e32 v158, v158, v159
	v_add_f32_e32 v250, v250, v251
	v_add_f32_e32 v158, v158, v250
	v_add_f32_e32 v161, v161, v158
	v_mul_f32_e32 v158, v166, v236
	v_mul_f32_e32 v159, v167, v237
	v_mul_f32_e32 v250, v168, v238
	v_mul_f32_e32 v251, v169, v239
	v_cvt_pk_bf16_f32 v158, v158, v159
	v_cvt_pk_bf16_f32 v159, v250, v251
	s_nop 1
	v_permlane16_swap_b32_e32 v156, v158
	v_permlane16_swap_b32_e32 v157, v159
	s_add_u32 s28, s22, 0x600800
	s_addc_u32 s29, s23, 0
	global_store_dwordx4 v254, v[156:159], s[28:29]
	ds_bpermute_b32 v158, v248, v161
	s_waitcnt lgkmcnt(0)
	v_add_f32_e32 v161, v161, v158
	ds_bpermute_b32 v158, v249, v161
	s_waitcnt lgkmcnt(0)
	v_add_f32_e32 v161, v161, v158
	global_store_dword v247, v161, s[30:31] offset:4
	s_add_u32 s26, s26, 0x10000
	s_addc_u32 s27, s27, 0
	s_add_u32 s30, s30, 0x400
	s_addc_u32 s31, s31, 0
	s_waitcnt vmcnt(25)
	v_add_f32_e32 v170, v132, v170
	v_add_f32_e32 v171, v133, v171
	v_add_f32_e32 v172, v134, v172
	v_add_f32_e32 v173, v135, v173
	global_store_dwordx4 v244, v[170:173], s[26:27]
	v_mul_f32_e32 v158, v170, v170
	v_mul_f32_e32 v159, v171, v171
	v_mul_f32_e32 v250, v172, v172
	v_mul_f32_e32 v251, v173, v173
	v_add_f32_e32 v158, v158, v159
	v_add_f32_e32 v250, v250, v251
	v_add_f32_e32 v161, v158, v250
	v_mul_f32_e32 v156, v170, v208
	v_mul_f32_e32 v157, v171, v209
	v_mul_f32_e32 v158, v172, v210
	v_mul_f32_e32 v159, v173, v211
	v_cvt_pk_bf16_f32 v156, v156, v157
	v_cvt_pk_bf16_f32 v157, v158, v159
	v_add_f32_e32 v174, v136, v174
	v_add_f32_e32 v175, v137, v175
	v_add_f32_e32 v176, v138, v176
	v_add_f32_e32 v177, v139, v177
	global_store_dwordx4 v244, v[174:177], s[26:27] offset:64
	v_mul_f32_e32 v158, v174, v174
	v_mul_f32_e32 v159, v175, v175
	v_mul_f32_e32 v250, v176, v176
	v_mul_f32_e32 v251, v177, v177
	v_add_f32_e32 v158, v158, v159
	v_add_f32_e32 v250, v250, v251
	v_add_f32_e32 v158, v158, v250
	v_add_f32_e32 v161, v161, v158
	v_mul_f32_e32 v158, v174, v212
	v_mul_f32_e32 v159, v175, v213
	v_mul_f32_e32 v250, v176, v214
	v_mul_f32_e32 v251, v177, v215
	v_cvt_pk_bf16_f32 v158, v158, v159
	v_cvt_pk_bf16_f32 v159, v250, v251
	s_nop 1
	v_permlane16_swap_b32_e32 v156, v158
	v_permlane16_swap_b32_e32 v157, v159
	s_add_u32 s28, s22, 0xc00
	s_addc_u32 s29, s23, 0
	global_store_dwordx4 v254, v[156:159], s[28:29]
	v_add_f32_e32 v178, v140, v178
	v_add_f32_e32 v179, v141, v179
	v_add_f32_e32 v180, v142, v180
	v_add_f32_e32 v181, v143, v181
	global_store_dwordx4 v244, v[178:181], s[26:27] offset:128
	v_mul_f32_e32 v158, v178, v178
	v_mul_f32_e32 v159, v179, v179
	v_mul_f32_e32 v250, v180, v180
	v_mul_f32_e32 v251, v181, v181
	v_add_f32_e32 v158, v158, v159
	v_add_f32_e32 v250, v250, v251
	v_add_f32_e32 v158, v158, v250
	v_add_f32_e32 v161, v161, v158
	v_mul_f32_e32 v156, v178, v216
	v_mul_f32_e32 v157, v179, v217
	v_mul_f32_e32 v158, v180, v218
	v_mul_f32_e32 v159, v181, v219
	v_cvt_pk_bf16_f32 v156, v156, v157
	v_cvt_pk_bf16_f32 v157, v158, v159
	v_add_f32_e32 v182, v144, v182
	v_add_f32_e32 v183, v145, v183
	v_add_f32_e32 v184, v146, v184
	v_add_f32_e32 v185, v147, v185
	global_store_dwordx4 v244, v[182:185], s[26:27] offset:192
	v_mul_f32_e32 v158, v182, v182
	v_mul_f32_e32 v159, v183, v183
	v_mul_f32_e32 v250, v184, v184
	v_mul_f32_e32 v251, v185, v185
	v_add_f32_e32 v158, v158, v159
	v_add_f32_e32 v250, v250, v251
	v_add_f32_e32 v158, v158, v250
	v_add_f32_e32 v161, v161, v158
	v_mul_f32_e32 v158, v182, v220
	v_mul_f32_e32 v159, v183, v221
	v_mul_f32_e32 v250, v184, v222
	v_mul_f32_e32 v251, v185, v223
	v_cvt_pk_bf16_f32 v158, v158, v159
	v_cvt_pk_bf16_f32 v159, v250, v251
	s_nop 1
	v_permlane16_swap_b32_e32 v156, v158
	v_permlane16_swap_b32_e32 v157, v159
	s_add_u32 s28, s22, 0x200c00
	s_addc_u32 s29, s23, 0
	global_store_dwordx4 v254, v[156:159], s[28:29]
	ds_bpermute_b32 v158, v248, v161
	s_waitcnt lgkmcnt(0)
	v_add_f32_e32 v161, v161, v158
	ds_bpermute_b32 v158, v249, v161
	s_waitcnt lgkmcnt(0)
	v_add_f32_e32 v161, v161, v158
	global_store_dword v247, v161, s[30:31]
	s_waitcnt vmcnt(21)
	v_add_f32_e32 v186, v92, v186
	v_add_f32_e32 v187, v93, v187
	v_add_f32_e32 v188, v94, v188
	v_add_f32_e32 v189, v95, v189
	global_store_dwordx4 v244, v[186:189], s[26:27] offset:256
	v_mul_f32_e32 v158, v186, v186
	v_mul_f32_e32 v159, v187, v187
	v_mul_f32_e32 v250, v188, v188
	v_mul_f32_e32 v251, v189, v189
	v_add_f32_e32 v158, v158, v159
	v_add_f32_e32 v250, v250, v251
	v_add_f32_e32 v161, v158, v250
	v_mul_f32_e32 v156, v186, v224
	v_mul_f32_e32 v157, v187, v225
	v_mul_f32_e32 v158, v188, v226
	v_mul_f32_e32 v159, v189, v227
	v_cvt_pk_bf16_f32 v156, v156, v157
	v_cvt_pk_bf16_f32 v157, v158, v159
	v_add_f32_e32 v190, v88, v190
	v_add_f32_e32 v191, v89, v191
	v_add_f32_e32 v192, v90, v192
	v_add_f32_e32 v193, v91, v193
	global_store_dwordx4 v244, v[190:193], s[26:27] offset:320
	v_mul_f32_e32 v158, v190, v190
	v_mul_f32_e32 v159, v191, v191
	v_mul_f32_e32 v250, v192, v192
	v_mul_f32_e32 v251, v193, v193
	v_add_f32_e32 v158, v158, v159
	v_add_f32_e32 v250, v250, v251
	v_add_f32_e32 v158, v158, v250
	v_add_f32_e32 v161, v161, v158
	v_mul_f32_e32 v158, v190, v228
	v_mul_f32_e32 v159, v191, v229
	v_mul_f32_e32 v250, v192, v230
	v_mul_f32_e32 v251, v193, v231
	v_cvt_pk_bf16_f32 v158, v158, v159
	v_cvt_pk_bf16_f32 v159, v250, v251
	s_nop 1
	v_permlane16_swap_b32_e32 v156, v158
	v_permlane16_swap_b32_e32 v157, v159
	s_add_u32 s28, s22, 0x400c00
	s_addc_u32 s29, s23, 0
	global_store_dwordx4 v254, v[156:159], s[28:29]
	v_add_f32_e32 v194, v76, v194
	v_add_f32_e32 v195, v77, v195
	v_add_f32_e32 v196, v78, v196
	v_add_f32_e32 v197, v79, v197
	global_store_dwordx4 v244, v[194:197], s[26:27] offset:384
	v_mul_f32_e32 v158, v194, v194
	v_mul_f32_e32 v159, v195, v195
	v_mul_f32_e32 v250, v196, v196
	v_mul_f32_e32 v251, v197, v197
	v_add_f32_e32 v158, v158, v159
	v_add_f32_e32 v250, v250, v251
	v_add_f32_e32 v158, v158, v250
	v_add_f32_e32 v161, v161, v158
	v_mul_f32_e32 v156, v194, v232
	v_mul_f32_e32 v157, v195, v233
	v_mul_f32_e32 v158, v196, v234
	v_mul_f32_e32 v159, v197, v235
	v_cvt_pk_bf16_f32 v156, v156, v157
	v_cvt_pk_bf16_f32 v157, v158, v159
	v_add_f32_e32 v240, v148, v240
	v_add_f32_e32 v241, v149, v241
	v_add_f32_e32 v242, v150, v242
	v_add_f32_e32 v243, v151, v243
	global_store_dwordx4 v244, v[240:243], s[26:27] offset:448
	v_mul_f32_e32 v158, v240, v240
	v_mul_f32_e32 v159, v241, v241
	v_mul_f32_e32 v250, v242, v242
	v_mul_f32_e32 v251, v243, v243
	v_add_f32_e32 v158, v158, v159
	v_add_f32_e32 v250, v250, v251
	v_add_f32_e32 v158, v158, v250
	v_add_f32_e32 v161, v161, v158
	v_mul_f32_e32 v158, v240, v236
	v_mul_f32_e32 v159, v241, v237
	v_mul_f32_e32 v250, v242, v238
	v_mul_f32_e32 v251, v243, v239
	v_cvt_pk_bf16_f32 v158, v158, v159
	v_cvt_pk_bf16_f32 v159, v250, v251
	s_nop 1
	v_permlane16_swap_b32_e32 v156, v158
	v_permlane16_swap_b32_e32 v157, v159
	s_add_u32 s28, s22, 0x600c00
	s_addc_u32 s29, s23, 0
	global_store_dwordx4 v254, v[156:159], s[28:29]
	ds_bpermute_b32 v158, v248, v161
	s_waitcnt lgkmcnt(0)
	v_add_f32_e32 v161, v161, v158
	ds_bpermute_b32 v158, v249, v161
	s_waitcnt lgkmcnt(0)
	v_add_f32_e32 v161, v161, v158
	global_store_dword v247, v161, s[30:31] offset:4
	s_add_u32 s26, s26, 0x10000
	s_addc_u32 s27, s27, 0
	s_add_u32 s30, s30, 0x400
	s_addc_u32 s31, s31, 0
	s_branch .LBB0_360

.Lproj_cd:
	s_or_b32 s4, s16, s67
	v_mov_b32 v10, v198
	v_ashrrev_i32_e32 v0, 2, v10
	s_lshl_b32 s4, s4, 7
	v_add_u32_e32 v2, s4, v0
	v_ashrrev_i32_e32 v3, 31, v2
	v_lshlrev_b64 v[2:3], 6, v[2:3]
	v_lshlrev_b32_e32 v1, 4, v10
	v_add_u32_e32 v4, s17, v0
	v_lshl_add_u64 v[2:3], s[96:97], 0, v[2:3]
	v_and_b32_e32 v152, 48, v1
	v_ashrrev_i32_e32 v5, 31, v4
	v_lshl_add_u64 v[2:3], v[2:3], 0, v[152:153]
	v_lshlrev_b64 v[4:5], 6, v[4:5]
	v_lshl_add_u64 v[156:157], s[8:9], 0, v[4:5]
	v_add_co_u32_e32 v6, vcc, s62, v2
	v_lshl_add_u64 v[4:5], v[156:157], 0, v[152:153]
	s_nop 0
	v_addc_co_u32_e32 v7, vcc, 0, v3, vcc
	v_add_co_u32_e32 v8, vcc, s62, v4
	s_and_b32 s7, s42, 56
	v_lshrrev_b32_e32 v1, 2, v10
	s_or_b32 s6, s67, s6
	v_addc_co_u32_e32 v9, vcc, 0, v5, vcc
	v_and_b32_e32 v12, 12, v1
	s_movk_i32 s20, 0x1230
	s_or_b32 s84, s6, s7
	v_add_co_u32_e32 v60, vcc, s33, v4
	v_lshrrev_b32_e64 v12, v12, s20
	s_lshl_b64 s[6:7], s[84:85], 18
	v_addc_co_u32_e32 v61, vcc, 0, v5, vcc
	v_and_b32_e32 v11, 3, v10
	v_ashrrev_i32_e32 v1, 31, v0
	v_xor_b32_e32 v10, v12, v10
	s_add_u32 s6, s82, s6
	v_add_co_u32_e32 v62, vcc, s72, v4
	v_lshlrev_b32_e32 v13, 6, v0
	v_lshlrev_b64 v[0:1], 11, v[0:1]
	v_lshlrev_b32_e32 v10, 4, v10
	s_addc_u32 s7, s83, s7
	v_addc_co_u32_e32 v63, vcc, 0, v5, vcc
	s_nop 0
	v_readfirstlane_b32 s26, v2
	v_readfirstlane_b32 s27, v3
	v_readfirstlane_b32 s28, v4
	v_readfirstlane_b32 s29, v5
	v_lshrrev_b32_e32 v250, 6, v198
	s_nop 0
	v_readfirstlane_b32 s24, v250
	s_lshl_b32 s24, s24, 10
	v_lshrrev_b32_e32 v250, 2, v200
	v_lshrrev_b32_e32 v251, 4, v200
	v_lshlrev_b32_e32 v251, 2, v251
	v_mov_b32_e32 v248, 0x1230
	v_lshrrev_b32_e32 v251, v251, v248
	v_xor_b32_e32 v251, v251, v200
	v_and_b32_e32 v251, 3, v251
	v_lshlrev_b32_e32 v251, 4, v251
	v_lshl_add_u32 v244, v250, 11, v251
	v_add_u32_e32 v245, 0x20000, v244
	v_add_u32_e32 v246, 0x40000, v244
	v_add_u32_e32 v247, 0x60000, v244
	v_lshl_add_u32 v156, v250, 6, v251
	v_add_u32_e32 v157, 0x1000, v156
	v_add_u32_e32 v158, 0x2000, v156
	v_add_u32_e32 v159, 0x3000, v156
	s_mov_b32 s25, 0
	s_add_u32 m0, s25, s24
	s_nop 0
	global_load_lds_dwordx4 v156, s[26:27]
	s_add_u32 m0, m0, 0x1000
	s_nop 0
	global_load_lds_dwordx4 v157, s[26:27]
	s_add_u32 m0, m0, 0x1000
	s_nop 0
	global_load_lds_dwordx4 v156, s[28:29]
	s_add_u32 m0, m0, 0x1000
	s_nop 0
	global_load_lds_dwordx4 v157, s[28:29]
	s_add_u32 m0, m0, 0x1000
	s_nop 0
	global_load_lds_dwordx4 v158, s[28:29]
	s_add_u32 m0, m0, 0x1000
	s_nop 0
	global_load_lds_dwordx4 v159, s[28:29]
	s_add_u32 s26, s26, 0x200000
	s_addc_u32 s27, s27, 0
	s_add_u32 s28, s28, 0x34000
	s_addc_u32 s29, s29, 0
	s_add_u32 s25, s25, 24576
	s_cmp_eq_u32 s25, 73728
	s_cselect_b32 s25, 0, s25
	s_add_u32 m0, s25, s24
	s_nop 0
	global_load_lds_dwordx4 v156, s[26:27]
	s_add_u32 m0, m0, 0x1000
	s_nop 0
	global_load_lds_dwordx4 v157, s[26:27]
	s_add_u32 m0, m0, 0x1000
	s_nop 0
	global_load_lds_dwordx4 v156, s[28:29]
	s_add_u32 m0, m0, 0x1000
	s_nop 0
	global_load_lds_dwordx4 v157, s[28:29]
	s_add_u32 m0, m0, 0x1000
	s_nop 0
	global_load_lds_dwordx4 v158, s[28:29]
	s_add_u32 m0, m0, 0x1000
	s_nop 0
	global_load_lds_dwordx4 v159, s[28:29]
	s_add_u32 s26, s26, 0x200000
	s_addc_u32 s27, s27, 0
	s_add_u32 s28, s28, 0x34000
	s_addc_u32 s29, s29, 0
	s_add_u32 s25, s25, 24576
	s_cmp_eq_u32 s25, 73728
	s_cselect_b32 s25, 0, s25
	s_add_u32 m0, s25, s24
	s_nop 0
	global_load_lds_dwordx4 v156, s[26:27]
	s_add_u32 m0, m0, 0x1000
	s_nop 0
	global_load_lds_dwordx4 v157, s[26:27]
	s_add_u32 m0, m0, 0x1000
	s_nop 0
	global_load_lds_dwordx4 v156, s[28:29]
	s_add_u32 m0, m0, 0x1000
	s_nop 0
	global_load_lds_dwordx4 v157, s[28:29]
	s_add_u32 m0, m0, 0x1000
	s_nop 0
	global_load_lds_dwordx4 v158, s[28:29]
	s_add_u32 m0, m0, 0x1000
	s_nop 0
	global_load_lds_dwordx4 v159, s[28:29]
	s_add_u32 s26, s26, 0x200000
	s_addc_u32 s27, s27, 0
	s_add_u32 s28, s28, 0x34000
	s_addc_u32 s29, s29, 0
	s_add_u32 s25, s25, 24576
	s_cmp_eq_u32 s25, 73728
	s_cselect_b32 s25, 0, s25
	v_mov_b32_e32 v24, 0
	v_mov_b32_e32 v25, v24
	v_mov_b32_e32 v26, v24
	v_mov_b32_e32 v27, v24
	v_mov_b32_e32 v28, v24
	v_mov_b32_e32 v29, v24
	v_mov_b32_e32 v30, v24
	v_mov_b32_e32 v31, v24
	v_mov_b32_e32 v32, v24
	v_mov_b32_e32 v33, v24
	v_mov_b32_e32 v34, v24
	v_mov_b32_e32 v35, v24
	v_mov_b32_e32 v64, v24
	v_mov_b32_e32 v65, v24
	v_mov_b32_e32 v66, v24
	v_mov_b32_e32 v67, v24
	v_mov_b32_e32 v68, v24
	v_mov_b32_e32 v69, v24
	v_mov_b32_e32 v70, v24
	v_mov_b32_e32 v71, v24
	v_mov_b32_e32 v60, v24
	v_mov_b32_e32 v61, v24
	v_mov_b32_e32 v62, v24
	v_mov_b32_e32 v63, v24
	v_mov_b32_e32 v100, v24
	v_mov_b32_e32 v101, v24
	v_mov_b32_e32 v102, v24
	v_mov_b32_e32 v103, v24
	v_mov_b32_e32 v104, v24
	v_mov_b32_e32 v105, v24
	v_mov_b32_e32 v106, v24
	v_mov_b32_e32 v107, v24
	v_mov_b32_e32 v120, v24
	v_mov_b32_e32 v121, v24
	v_mov_b32_e32 v122, v24
	v_mov_b32_e32 v36, v24
	v_mov_b32_e32 v37, v24
	v_mov_b32_e32 v38, v24
	v_mov_b32_e32 v39, v24
	v_mov_b32_e32 v52, v24
	v_mov_b32_e32 v53, v24
	v_mov_b32_e32 v54, v24
	v_mov_b32_e32 v55, v24
	v_mov_b32_e32 v56, v24
	v_mov_b32_e32 v57, v24
	v_mov_b32_e32 v58, v24
	v_mov_b32_e32 v59, v24
	v_mov_b32_e32 v40, v24
	v_mov_b32_e32 v41, v24
	v_mov_b32_e32 v42, v24
	v_mov_b32_e32 v43, v24
	v_mov_b32_e32 v44, v24
	v_mov_b32_e32 v45, v24
	v_mov_b32_e32 v46, v24
	v_mov_b32_e32 v47, v24
	v_mov_b32_e32 v48, v24
	v_mov_b32_e32 v49, v24
	v_mov_b32_e32 v50, v24
	v_mov_b32_e32 v51, v24
	v_mov_b32_e32 v123, v24
	v_mov_b32_e32 v128, v24
	v_mov_b32_e32 v129, v24
	v_mov_b32_e32 v130, v24
	v_mov_b32_e32 v131, v24
	v_mov_b32_e32 v108, v24
	v_mov_b32_e32 v109, v24
	v_mov_b32_e32 v110, v24
	v_mov_b32_e32 v111, v24
	v_mov_b32_e32 v112, v24
	v_mov_b32_e32 v113, v24
	v_mov_b32_e32 v114, v24
	v_mov_b32_e32 v115, v24
	v_mov_b32_e32 v116, v24
	v_mov_b32_e32 v117, v24
	v_mov_b32_e32 v118, v24
	v_mov_b32_e32 v119, v24
	v_mov_b32_e32 v124, v24
	v_mov_b32_e32 v125, v24
	v_mov_b32_e32 v126, v24
	v_mov_b32_e32 v127, v24
	v_mov_b32_e32 v80, v24
	v_mov_b32_e32 v81, v24
	v_mov_b32_e32 v82, v24
	v_mov_b32_e32 v83, v24
	v_mov_b32_e32 v88, v24
	v_mov_b32_e32 v89, v24
	v_mov_b32_e32 v90, v24
	v_mov_b32_e32 v91, v24
	v_mov_b32_e32 v92, v24
	v_mov_b32_e32 v93, v24
	v_mov_b32_e32 v94, v24
	v_mov_b32_e32 v95, v24
	v_mov_b32_e32 v76, v24
	v_mov_b32_e32 v77, v24
	v_mov_b32_e32 v78, v24
	v_mov_b32_e32 v79, v24
	v_mov_b32_e32 v132, v24
	v_mov_b32_e32 v133, v24
	v_mov_b32_e32 v134, v24
	v_mov_b32_e32 v135, v24
	v_mov_b32_e32 v136, v24
	v_mov_b32_e32 v137, v24
	v_mov_b32_e32 v138, v24
	v_mov_b32_e32 v139, v24
	v_mov_b32_e32 v140, v24
	v_mov_b32_e32 v141, v24
	v_mov_b32_e32 v142, v24
	v_mov_b32_e32 v143, v24
	v_mov_b32_e32 v144, v24
	v_mov_b32_e32 v145, v24
	v_mov_b32_e32 v146, v24
	v_mov_b32_e32 v147, v24
	v_mov_b32_e32 v96, v24
	v_mov_b32_e32 v97, v24
	v_mov_b32_e32 v98, v24
	v_mov_b32_e32 v99, v24
	v_mov_b32_e32 v84, v24
	v_mov_b32_e32 v85, v24
	v_mov_b32_e32 v86, v24
	v_mov_b32_e32 v87, v24
	v_mov_b32_e32 v72, v24
	v_mov_b32_e32 v73, v24
	v_mov_b32_e32 v74, v24
	v_mov_b32_e32 v75, v24
	v_mov_b32_e32 v148, v24
	v_mov_b32_e32 v149, v24
	v_mov_b32_e32 v150, v24
	v_mov_b32_e32 v151, v24
	s_waitcnt vmcnt(12)
	s_barrier
	s_mov_b32 s30, 0
	v_add_u32_e32 v248, s30, v155
	v_add_u32_e32 v249, s30, v160
	ds_read_b128 v[186:189], v248
	ds_read_b128 v[212:215], v249 offset:8192
	ds_read_b128 v[190:193], v248 offset:1024
	ds_read_b128 v[216:219], v249 offset:9216
	ds_read_b128 v[194:197], v248 offset:2048
	ds_read_b128 v[220:223], v249 offset:10240
	ds_read_b128 v[208:211], v248 offset:3072
	ds_read_b128 v[224:227], v249 offset:11264
	ds_read_b128 v[228:231], v249 offset:12288
	ds_read_b128 v[232:235], v249 offset:13312
	ds_read_b128 v[236:239], v249 offset:14336
	ds_read_b128 v[240:243], v249 offset:15360
	s_add_u32 s30, s30, 24576
	s_cmp_eq_u32 s30, 73728
	s_cselect_b32 s30, 0, s30
	s_waitcnt vmcnt(6)
	s_waitcnt lgkmcnt(0)
	s_barrier
	s_mov_b32 s31, 14
	s_cmpk_lt_u32 s43, 0x180
	s_cbranch_scc0 .Lgm3_cheap
.Lgm3_loop:
	v_add_u32_e32 v248, s30, v155
	v_add_u32_e32 v249, s30, v160
	v_mfma_f32_16x16x32_bf16 v[128:131], v[212:215], v[186:189], v[128:131]
	ds_read_b128 v[0:3], v248
	v_mfma_f32_16x16x32_bf16 v[68:71], v[212:215], v[190:193], v[68:71]
	ds_read_b128 v[16:19], v249 offset:8192
	v_mfma_f32_16x16x32_bf16 v[108:111], v[212:215], v[194:197], v[108:111]
	ds_read_b128 v[4:7], v248 offset:1024
	v_mfma_f32_16x16x32_bf16 v[132:135], v[212:215], v[208:211], v[132:135]
	ds_read_b128 v[20:23], v249 offset:9216
	v_mfma_f32_16x16x32_bf16 v[120:123], v[216:219], v[186:189], v[120:123]
	ds_read_b128 v[8:11], v248 offset:2048
	v_mfma_f32_16x16x32_bf16 v[64:67], v[216:219], v[190:193], v[64:67]
	ds_read_b128 v[162:165], v249 offset:10240
	v_mfma_f32_16x16x32_bf16 v[112:115], v[216:219], v[194:197], v[112:115]
	ds_read_b128 v[12:15], v248 offset:3072
	v_mfma_f32_16x16x32_bf16 v[136:139], v[216:219], v[208:211], v[136:139]
	ds_read_b128 v[166:169], v249 offset:11264
	v_mfma_f32_16x16x32_bf16 v[104:107], v[220:223], v[186:189], v[104:107]
	ds_read_b128 v[170:173], v249 offset:12288
	v_mfma_f32_16x16x32_bf16 v[56:59], v[220:223], v[190:193], v[56:59]
	ds_read_b128 v[174:177], v249 offset:13312
	v_mfma_f32_16x16x32_bf16 v[116:119], v[220:223], v[194:197], v[116:119]
	ds_read_b128 v[178:181], v249 offset:14336
	v_mfma_f32_16x16x32_bf16 v[140:143], v[220:223], v[208:211], v[140:143]
	ds_read_b128 v[182:185], v249 offset:15360
	s_add_u32 m0, s25, s24
	v_mfma_f32_16x16x32_bf16 v[100:103], v[224:227], v[186:189], v[100:103]
	global_load_lds_dwordx4 v156, s[26:27]
	v_mfma_f32_16x16x32_bf16 v[52:55], v[224:227], v[190:193], v[52:55]
	v_mfma_f32_16x16x32_bf16 v[124:127], v[224:227], v[194:197], v[124:127]
	s_add_u32 m0, m0, 0x1000
	v_mfma_f32_16x16x32_bf16 v[144:147], v[224:227], v[208:211], v[144:147]
	global_load_lds_dwordx4 v157, s[26:27]
	v_mfma_f32_16x16x32_bf16 v[60:63], v[228:231], v[186:189], v[60:63]
	v_mfma_f32_16x16x32_bf16 v[36:39], v[228:231], v[190:193], v[36:39]
	s_add_u32 m0, m0, 0x1000
	v_mfma_f32_16x16x32_bf16 v[80:83], v[228:231], v[194:197], v[80:83]
	global_load_lds_dwordx4 v156, s[28:29]
	v_mfma_f32_16x16x32_bf16 v[96:99], v[228:231], v[208:211], v[96:99]
	v_mfma_f32_16x16x32_bf16 v[48:51], v[232:235], v[186:189], v[48:51]
	s_add_u32 m0, m0, 0x1000
	v_mfma_f32_16x16x32_bf16 v[32:35], v[232:235], v[190:193], v[32:35]
	global_load_lds_dwordx4 v157, s[28:29]
	v_mfma_f32_16x16x32_bf16 v[88:91], v[232:235], v[194:197], v[88:91]
	v_mfma_f32_16x16x32_bf16 v[84:87], v[232:235], v[208:211], v[84:87]
	s_add_u32 m0, m0, 0x1000
	v_mfma_f32_16x16x32_bf16 v[44:47], v[236:239], v[186:189], v[44:47]
	global_load_lds_dwordx4 v158, s[28:29]
	v_mfma_f32_16x16x32_bf16 v[28:31], v[236:239], v[190:193], v[28:31]
	v_mfma_f32_16x16x32_bf16 v[92:95], v[236:239], v[194:197], v[92:95]
	s_add_u32 m0, m0, 0x1000
	v_mfma_f32_16x16x32_bf16 v[72:75], v[236:239], v[208:211], v[72:75]
	global_load_lds_dwordx4 v159, s[28:29]
	v_mfma_f32_16x16x32_bf16 v[40:43], v[240:243], v[186:189], v[40:43]
	v_mfma_f32_16x16x32_bf16 v[24:27], v[240:243], v[190:193], v[24:27]
	v_mfma_f32_16x16x32_bf16 v[76:79], v[240:243], v[194:197], v[76:79]
	v_mfma_f32_16x16x32_bf16 v[148:151], v[240:243], v[208:211], v[148:151]
	s_add_u32 s26, s26, 0x200000
	s_addc_u32 s27, s27, 0
	s_add_u32 s28, s28, 0x34000
	s_addc_u32 s29, s29, 0
	s_add_u32 s25, s25, 24576
	s_cmp_eq_u32 s25, 73728
	s_cselect_b32 s25, 0, s25
	s_add_u32 s30, s30, 24576
	s_cmp_eq_u32 s30, 73728
	s_cselect_b32 s30, 0, s30
	s_waitcnt vmcnt(6)
	s_waitcnt lgkmcnt(0)
	s_barrier
	v_add_u32_e32 v248, s30, v155
	v_add_u32_e32 v249, s30, v160
	v_mfma_f32_16x16x32_bf16 v[128:131], v[16:19], v[0:3], v[128:131]
	ds_read_b128 v[186:189], v248
	v_mfma_f32_16x16x32_bf16 v[68:71], v[16:19], v[4:7], v[68:71]
	ds_read_b128 v[212:215], v249 offset:8192
	v_mfma_f32_16x16x32_bf16 v[108:111], v[16:19], v[8:11], v[108:111]
	ds_read_b128 v[190:193], v248 offset:1024
	v_mfma_f32_16x16x32_bf16 v[132:135], v[16:19], v[12:15], v[132:135]
	ds_read_b128 v[216:219], v249 offset:9216
	v_mfma_f32_16x16x32_bf16 v[120:123], v[20:23], v[0:3], v[120:123]
	ds_read_b128 v[194:197], v248 offset:2048
	v_mfma_f32_16x16x32_bf16 v[64:67], v[20:23], v[4:7], v[64:67]
	ds_read_b128 v[220:223], v249 offset:10240
	v_mfma_f32_16x16x32_bf16 v[112:115], v[20:23], v[8:11], v[112:115]
	ds_read_b128 v[208:211], v248 offset:3072
	v_mfma_f32_16x16x32_bf16 v[136:139], v[20:23], v[12:15], v[136:139]
	ds_read_b128 v[224:227], v249 offset:11264
	v_mfma_f32_16x16x32_bf16 v[104:107], v[162:165], v[0:3], v[104:107]
	ds_read_b128 v[228:231], v249 offset:12288
	v_mfma_f32_16x16x32_bf16 v[56:59], v[162:165], v[4:7], v[56:59]
	ds_read_b128 v[232:235], v249 offset:13312
	v_mfma_f32_16x16x32_bf16 v[116:119], v[162:165], v[8:11], v[116:119]
	ds_read_b128 v[236:239], v249 offset:14336
	v_mfma_f32_16x16x32_bf16 v[140:143], v[162:165], v[12:15], v[140:143]
	ds_read_b128 v[240:243], v249 offset:15360
	s_add_u32 m0, s25, s24
	v_mfma_f32_16x16x32_bf16 v[100:103], v[166:169], v[0:3], v[100:103]
	global_load_lds_dwordx4 v156, s[26:27]
	v_mfma_f32_16x16x32_bf16 v[52:55], v[166:169], v[4:7], v[52:55]
	v_mfma_f32_16x16x32_bf16 v[124:127], v[166:169], v[8:11], v[124:127]
	s_add_u32 m0, m0, 0x1000
	v_mfma_f32_16x16x32_bf16 v[144:147], v[166:169], v[12:15], v[144:147]
	global_load_lds_dwordx4 v157, s[26:27]
	v_mfma_f32_16x16x32_bf16 v[60:63], v[170:173], v[0:3], v[60:63]
	v_mfma_f32_16x16x32_bf16 v[36:39], v[170:173], v[4:7], v[36:39]
	s_add_u32 m0, m0, 0x1000
	v_mfma_f32_16x16x32_bf16 v[80:83], v[170:173], v[8:11], v[80:83]
	global_load_lds_dwordx4 v156, s[28:29]
	v_mfma_f32_16x16x32_bf16 v[96:99], v[170:173], v[12:15], v[96:99]
	v_mfma_f32_16x16x32_bf16 v[48:51], v[174:177], v[0:3], v[48:51]
	s_add_u32 m0, m0, 0x1000
	v_mfma_f32_16x16x32_bf16 v[32:35], v[174:177], v[4:7], v[32:35]
	global_load_lds_dwordx4 v157, s[28:29]
	v_mfma_f32_16x16x32_bf16 v[88:91], v[174:177], v[8:11], v[88:91]
	v_mfma_f32_16x16x32_bf16 v[84:87], v[174:177], v[12:15], v[84:87]
	s_add_u32 m0, m0, 0x1000
	v_mfma_f32_16x16x32_bf16 v[44:47], v[178:181], v[0:3], v[44:47]
	global_load_lds_dwordx4 v158, s[28:29]
	v_mfma_f32_16x16x32_bf16 v[28:31], v[178:181], v[4:7], v[28:31]
	v_mfma_f32_16x16x32_bf16 v[92:95], v[178:181], v[8:11], v[92:95]
	s_add_u32 m0, m0, 0x1000
	v_mfma_f32_16x16x32_bf16 v[72:75], v[178:181], v[12:15], v[72:75]
	global_load_lds_dwordx4 v159, s[28:29]
	v_mfma_f32_16x16x32_bf16 v[40:43], v[182:185], v[0:3], v[40:43]
	v_mfma_f32_16x16x32_bf16 v[24:27], v[182:185], v[4:7], v[24:27]
	v_mfma_f32_16x16x32_bf16 v[76:79], v[182:185], v[8:11], v[76:79]
	v_mfma_f32_16x16x32_bf16 v[148:151], v[182:185], v[12:15], v[148:151]
	s_add_u32 s26, s26, 0x200000
	s_addc_u32 s27, s27, 0
	s_add_u32 s28, s28, 0x34000
	s_addc_u32 s29, s29, 0
	s_add_u32 s25, s25, 24576
	s_cmp_eq_u32 s25, 73728
	s_cselect_b32 s25, 0, s25
	s_add_u32 s30, s30, 24576
	s_cmp_eq_u32 s30, 73728
	s_cselect_b32 s30, 0, s30
	s_waitcnt vmcnt(6)
	s_waitcnt lgkmcnt(0)
	s_barrier
	s_sub_u32 s31, s31, 1
	s_cmp_lg_u32 s31, 0
	s_cbranch_scc1 .Lgm3_loop
	v_add_u32_e32 v248, s30, v155
	v_add_u32_e32 v249, s30, v160
	v_mfma_f32_16x16x32_bf16 v[128:131], v[212:215], v[186:189], v[128:131]
	ds_read_b128 v[0:3], v248
	v_mfma_f32_16x16x32_bf16 v[68:71], v[212:215], v[190:193], v[68:71]
	ds_read_b128 v[16:19], v249 offset:8192
	v_mfma_f32_16x16x32_bf16 v[108:111], v[212:215], v[194:197], v[108:111]
	ds_read_b128 v[4:7], v248 offset:1024
	v_mfma_f32_16x16x32_bf16 v[132:135], v[212:215], v[208:211], v[132:135]
	ds_read_b128 v[20:23], v249 offset:9216
	v_mfma_f32_16x16x32_bf16 v[120:123], v[216:219], v[186:189], v[120:123]
	ds_read_b128 v[8:11], v248 offset:2048
	v_mfma_f32_16x16x32_bf16 v[64:67], v[216:219], v[190:193], v[64:67]
	ds_read_b128 v[162:165], v249 offset:10240
	v_mfma_f32_16x16x32_bf16 v[112:115], v[216:219], v[194:197], v[112:115]
	ds_read_b128 v[12:15], v248 offset:3072
	v_mfma_f32_16x16x32_bf16 v[136:139], v[216:219], v[208:211], v[136:139]
	ds_read_b128 v[166:169], v249 offset:11264
	v_mfma_f32_16x16x32_bf16 v[104:107], v[220:223], v[186:189], v[104:107]
	ds_read_b128 v[170:173], v249 offset:12288
	v_mfma_f32_16x16x32_bf16 v[56:59], v[220:223], v[190:193], v[56:59]
	ds_read_b128 v[174:177], v249 offset:13312
	v_mfma_f32_16x16x32_bf16 v[116:119], v[220:223], v[194:197], v[116:119]
	ds_read_b128 v[178:181], v249 offset:14336
	v_mfma_f32_16x16x32_bf16 v[140:143], v[220:223], v[208:211], v[140:143]
	ds_read_b128 v[182:185], v249 offset:15360
	s_add_u32 m0, s25, s24
	v_mfma_f32_16x16x32_bf16 v[100:103], v[224:227], v[186:189], v[100:103]
	global_load_lds_dwordx4 v156, s[26:27]
	v_mfma_f32_16x16x32_bf16 v[52:55], v[224:227], v[190:193], v[52:55]
	v_mfma_f32_16x16x32_bf16 v[124:127], v[224:227], v[194:197], v[124:127]
	s_add_u32 m0, m0, 0x1000
	v_mfma_f32_16x16x32_bf16 v[144:147], v[224:227], v[208:211], v[144:147]
	global_load_lds_dwordx4 v157, s[26:27]
	v_mfma_f32_16x16x32_bf16 v[60:63], v[228:231], v[186:189], v[60:63]
	v_mfma_f32_16x16x32_bf16 v[36:39], v[228:231], v[190:193], v[36:39]
	s_add_u32 m0, m0, 0x1000
	v_mfma_f32_16x16x32_bf16 v[80:83], v[228:231], v[194:197], v[80:83]
	global_load_lds_dwordx4 v156, s[28:29]
	v_mfma_f32_16x16x32_bf16 v[96:99], v[228:231], v[208:211], v[96:99]
	v_mfma_f32_16x16x32_bf16 v[48:51], v[232:235], v[186:189], v[48:51]
	s_add_u32 m0, m0, 0x1000
	v_mfma_f32_16x16x32_bf16 v[32:35], v[232:235], v[190:193], v[32:35]
	global_load_lds_dwordx4 v157, s[28:29]
	v_mfma_f32_16x16x32_bf16 v[88:91], v[232:235], v[194:197], v[88:91]
	v_mfma_f32_16x16x32_bf16 v[84:87], v[232:235], v[208:211], v[84:87]
	s_add_u32 m0, m0, 0x1000
	v_mfma_f32_16x16x32_bf16 v[44:47], v[236:239], v[186:189], v[44:47]
	global_load_lds_dwordx4 v158, s[28:29]
	v_mfma_f32_16x16x32_bf16 v[28:31], v[236:239], v[190:193], v[28:31]
	v_mfma_f32_16x16x32_bf16 v[92:95], v[236:239], v[194:197], v[92:95]
	s_add_u32 m0, m0, 0x1000
	v_mfma_f32_16x16x32_bf16 v[72:75], v[236:239], v[208:211], v[72:75]
	global_load_lds_dwordx4 v159, s[28:29]
	v_mfma_f32_16x16x32_bf16 v[40:43], v[240:243], v[186:189], v[40:43]
	v_mfma_f32_16x16x32_bf16 v[24:27], v[240:243], v[190:193], v[24:27]
	v_mfma_f32_16x16x32_bf16 v[76:79], v[240:243], v[194:197], v[76:79]
	v_mfma_f32_16x16x32_bf16 v[148:151], v[240:243], v[208:211], v[148:151]
	s_add_u32 s26, s26, 0x200000
	s_addc_u32 s27, s27, 0
	s_add_u32 s28, s28, 0x34000
	s_addc_u32 s29, s29, 0
	s_add_u32 s25, s25, 24576
	s_cmp_eq_u32 s25, 73728
	s_cselect_b32 s25, 0, s25
	s_add_u32 s30, s30, 24576
	s_cmp_eq_u32 s30, 73728
	s_cselect_b32 s30, 0, s30
	s_waitcnt vmcnt(6)
	s_waitcnt lgkmcnt(0)
	s_barrier
	v_mfma_f32_16x16x32_bf16 v[128:131], v[16:19], v[0:3], v[128:131]
	v_mfma_f32_16x16x32_bf16 v[68:71], v[16:19], v[4:7], v[68:71]
	v_mfma_f32_16x16x32_bf16 v[108:111], v[16:19], v[8:11], v[108:111]
	v_mfma_f32_16x16x32_bf16 v[132:135], v[16:19], v[12:15], v[132:135]
	v_mfma_f32_16x16x32_bf16 v[120:123], v[20:23], v[0:3], v[120:123]
	v_mfma_f32_16x16x32_bf16 v[64:67], v[20:23], v[4:7], v[64:67]
	v_mfma_f32_16x16x32_bf16 v[112:115], v[20:23], v[8:11], v[112:115]
	v_mfma_f32_16x16x32_bf16 v[136:139], v[20:23], v[12:15], v[136:139]
	v_mfma_f32_16x16x32_bf16 v[104:107], v[162:165], v[0:3], v[104:107]
	v_mfma_f32_16x16x32_bf16 v[56:59], v[162:165], v[4:7], v[56:59]
	v_mfma_f32_16x16x32_bf16 v[116:119], v[162:165], v[8:11], v[116:119]
	v_mfma_f32_16x16x32_bf16 v[140:143], v[162:165], v[12:15], v[140:143]
	v_mfma_f32_16x16x32_bf16 v[100:103], v[166:169], v[0:3], v[100:103]
	v_mfma_f32_16x16x32_bf16 v[52:55], v[166:169], v[4:7], v[52:55]
	v_mfma_f32_16x16x32_bf16 v[124:127], v[166:169], v[8:11], v[124:127]
	v_mfma_f32_16x16x32_bf16 v[144:147], v[166:169], v[12:15], v[144:147]
	v_mfma_f32_16x16x32_bf16 v[60:63], v[170:173], v[0:3], v[60:63]
	v_mfma_f32_16x16x32_bf16 v[36:39], v[170:173], v[4:7], v[36:39]
	v_mfma_f32_16x16x32_bf16 v[80:83], v[170:173], v[8:11], v[80:83]
	v_mfma_f32_16x16x32_bf16 v[96:99], v[170:173], v[12:15], v[96:99]
	v_mfma_f32_16x16x32_bf16 v[48:51], v[174:177], v[0:3], v[48:51]
	v_mfma_f32_16x16x32_bf16 v[32:35], v[174:177], v[4:7], v[32:35]
	v_mfma_f32_16x16x32_bf16 v[88:91], v[174:177], v[8:11], v[88:91]
	v_mfma_f32_16x16x32_bf16 v[84:87], v[174:177], v[12:15], v[84:87]
	v_mfma_f32_16x16x32_bf16 v[44:47], v[178:181], v[0:3], v[44:47]
	v_mfma_f32_16x16x32_bf16 v[28:31], v[178:181], v[4:7], v[28:31]
	v_mfma_f32_16x16x32_bf16 v[92:95], v[178:181], v[8:11], v[92:95]
	v_mfma_f32_16x16x32_bf16 v[72:75], v[178:181], v[12:15], v[72:75]
	v_mfma_f32_16x16x32_bf16 v[40:43], v[182:185], v[0:3], v[40:43]
	v_mfma_f32_16x16x32_bf16 v[24:27], v[182:185], v[4:7], v[24:27]
	v_mfma_f32_16x16x32_bf16 v[76:79], v[182:185], v[8:11], v[76:79]
	v_mfma_f32_16x16x32_bf16 v[148:151], v[182:185], v[12:15], v[148:151]
	s_waitcnt vmcnt(0)
	s_waitcnt lgkmcnt(0)
	s_barrier
	s_branch .Lgm3_tail
.Lgm3_cheap:
	v_add_u32_e32 v248, s30, v155
	v_add_u32_e32 v249, s30, v160
	v_mfma_f32_16x16x32_bf16 v[128:131], v[212:215], v[186:189], v[128:131]
	ds_read_b128 v[0:3], v248
	v_mfma_f32_16x16x32_bf16 v[68:71], v[212:215], v[190:193], v[68:71]
	ds_read_b128 v[16:19], v249 offset:8192
	v_mfma_f32_16x16x32_bf16 v[108:111], v[212:215], v[194:197], v[108:111]
	ds_read_b128 v[4:7], v248 offset:1024
	v_mfma_f32_16x16x32_bf16 v[132:135], v[212:215], v[208:211], v[132:135]
	ds_read_b128 v[20:23], v249 offset:9216
	v_mfma_f32_16x16x32_bf16 v[120:123], v[216:219], v[186:189], v[120:123]
	ds_read_b128 v[8:11], v248 offset:2048
	s_add_u32 m0, s25, s24
	v_mfma_f32_16x16x32_bf16 v[64:67], v[216:219], v[190:193], v[64:67]
	ds_read_b128 v[12:15], v248 offset:3072
	global_load_lds_dwordx4 v156, s[26:27]
	s_add_u32 m0, m0, 0x1000
	v_mfma_f32_16x16x32_bf16 v[112:115], v[216:219], v[194:197], v[112:115]
	global_load_lds_dwordx4 v157, s[26:27]
	s_add_u32 m0, m0, 0x1000
	v_mfma_f32_16x16x32_bf16 v[136:139], v[216:219], v[208:211], v[136:139]
	global_load_lds_dwordx4 v156, s[28:29]
	s_add_u32 s26, s26, 0x200000
	s_addc_u32 s27, s27, 0
	s_add_u32 s28, s28, 0x34000
	s_addc_u32 s29, s29, 0
	s_add_u32 s25, s25, 24576
	s_cmp_eq_u32 s25, 73728
	s_cselect_b32 s25, 0, s25
	s_add_u32 s30, s30, 24576
	s_cmp_eq_u32 s30, 73728
	s_cselect_b32 s30, 0, s30
	s_waitcnt vmcnt(3)
	s_waitcnt lgkmcnt(0)
	s_barrier
	v_add_u32_e32 v248, s30, v155
	v_add_u32_e32 v249, s30, v160
	v_mfma_f32_16x16x32_bf16 v[128:131], v[16:19], v[0:3], v[128:131]
	ds_read_b128 v[186:189], v248
	v_mfma_f32_16x16x32_bf16 v[68:71], v[16:19], v[4:7], v[68:71]
	ds_read_b128 v[212:215], v249 offset:8192
	v_mfma_f32_16x16x32_bf16 v[108:111], v[16:19], v[8:11], v[108:111]
	ds_read_b128 v[190:193], v248 offset:1024
	v_mfma_f32_16x16x32_bf16 v[132:135], v[16:19], v[12:15], v[132:135]
	ds_read_b128 v[216:219], v249 offset:9216
	v_mfma_f32_16x16x32_bf16 v[120:123], v[20:23], v[0:3], v[120:123]
	ds_read_b128 v[194:197], v248 offset:2048
	s_add_u32 m0, s25, s24
	v_mfma_f32_16x16x32_bf16 v[64:67], v[20:23], v[4:7], v[64:67]
	ds_read_b128 v[208:211], v248 offset:3072
	global_load_lds_dwordx4 v156, s[26:27]
	s_add_u32 m0, m0, 0x1000
	v_mfma_f32_16x16x32_bf16 v[112:115], v[20:23], v[8:11], v[112:115]
	global_load_lds_dwordx4 v157, s[26:27]
	s_add_u32 m0, m0, 0x1000
	v_mfma_f32_16x16x32_bf16 v[136:139], v[20:23], v[12:15], v[136:139]
	global_load_lds_dwordx4 v156, s[28:29]
	s_add_u32 s26, s26, 0x200000
	s_addc_u32 s27, s27, 0
	s_add_u32 s28, s28, 0x34000
	s_addc_u32 s29, s29, 0
	s_add_u32 s25, s25, 24576
	s_cmp_eq_u32 s25, 73728
	s_cselect_b32 s25, 0, s25
	s_add_u32 s30, s30, 24576
	s_cmp_eq_u32 s30, 73728
	s_cselect_b32 s30, 0, s30
	s_waitcnt vmcnt(3)
	s_waitcnt lgkmcnt(0)
	s_barrier
	s_sub_u32 s31, s31, 1
	s_cmp_lg_u32 s31, 0
	s_cbranch_scc1 .Lgm3_cheap
	v_add_u32_e32 v248, s30, v155
	v_add_u32_e32 v249, s30, v160
	v_mfma_f32_16x16x32_bf16 v[128:131], v[212:215], v[186:189], v[128:131]
	ds_read_b128 v[0:3], v248
	v_mfma_f32_16x16x32_bf16 v[68:71], v[212:215], v[190:193], v[68:71]
	ds_read_b128 v[16:19], v249 offset:8192
	v_mfma_f32_16x16x32_bf16 v[108:111], v[212:215], v[194:197], v[108:111]
	ds_read_b128 v[4:7], v248 offset:1024
	v_mfma_f32_16x16x32_bf16 v[132:135], v[212:215], v[208:211], v[132:135]
	ds_read_b128 v[20:23], v249 offset:9216
	v_mfma_f32_16x16x32_bf16 v[120:123], v[216:219], v[186:189], v[120:123]
	ds_read_b128 v[8:11], v248 offset:2048
	s_add_u32 m0, s25, s24
	v_mfma_f32_16x16x32_bf16 v[64:67], v[216:219], v[190:193], v[64:67]
	ds_read_b128 v[12:15], v248 offset:3072
	global_load_lds_dwordx4 v156, s[26:27]
	s_add_u32 m0, m0, 0x1000
	v_mfma_f32_16x16x32_bf16 v[112:115], v[216:219], v[194:197], v[112:115]
	global_load_lds_dwordx4 v157, s[26:27]
	s_add_u32 m0, m0, 0x1000
	v_mfma_f32_16x16x32_bf16 v[136:139], v[216:219], v[208:211], v[136:139]
	global_load_lds_dwordx4 v156, s[28:29]
	s_add_u32 s26, s26, 0x200000
	s_addc_u32 s27, s27, 0
	s_add_u32 s28, s28, 0x34000
	s_addc_u32 s29, s29, 0
	s_add_u32 s25, s25, 24576
	s_cmp_eq_u32 s25, 73728
	s_cselect_b32 s25, 0, s25
	s_add_u32 s30, s30, 24576
	s_cmp_eq_u32 s30, 73728
	s_cselect_b32 s30, 0, s30
	s_waitcnt vmcnt(3)
	s_waitcnt lgkmcnt(0)
	s_barrier
	v_mfma_f32_16x16x32_bf16 v[128:131], v[16:19], v[0:3], v[128:131]
	v_mfma_f32_16x16x32_bf16 v[68:71], v[16:19], v[4:7], v[68:71]
	v_mfma_f32_16x16x32_bf16 v[108:111], v[16:19], v[8:11], v[108:111]
	v_mfma_f32_16x16x32_bf16 v[132:135], v[16:19], v[12:15], v[132:135]
	v_mfma_f32_16x16x32_bf16 v[120:123], v[20:23], v[0:3], v[120:123]
	v_mfma_f32_16x16x32_bf16 v[64:67], v[20:23], v[4:7], v[64:67]
	v_mfma_f32_16x16x32_bf16 v[112:115], v[20:23], v[8:11], v[112:115]
	v_mfma_f32_16x16x32_bf16 v[136:139], v[20:23], v[12:15], v[136:139]
	s_waitcnt vmcnt(0)
	s_waitcnt lgkmcnt(0)
	s_barrier

.LBB0_718:
	s_mov_b64 s[4:5], exec
	s_load_dword s13, s[88:89], 0x0
	v_lshrrev_b32_e32 v0, 6, v198
	v_lshlrev_b32_e32 v58, 4, v200
	v_readfirstlane_b32 s12, v0
	v_and_b32_e32 v59, 7, v200
	v_lshlrev_b32_e32 v59, 3, v59
	v_lshrrev_b32_e32 v1, 3, v200
	v_lshl_add_u32 v59, v1, 21, v59
	v_readlane_b32 s8, v253, 63
	s_nop 0
	s_add_u32 s12, s12, s8
	s_cmp_lt_u32 s12, 0x8000
	s_cbranch_scc0 .LBB0_721
	v_xor_b32_e32 v52, 32, v200
	v_lshlrev_b32_e32 v52, 2, v52
	v_xor_b32_e32 v53, 16, v200
	v_lshlrev_b32_e32 v53, 2, v53
	v_xor_b32_e32 v54, 8, v200
	v_lshlrev_b32_e32 v54, 2, v54
	v_xor_b32_e32 v55, 4, v200
	v_lshlrev_b32_e32 v55, 2, v55
	v_xor_b32_e32 v56, 2, v200
	v_lshlrev_b32_e32 v56, 2, v56
	v_xor_b32_e32 v57, 1, v200
	v_lshlrev_b32_e32 v57, 2, v57
	global_load_dwordx4 v[2:5], v58, s[46:47]
	global_load_dwordx4 v[6:9], v58, s[46:47] offset:1024
	global_load_dwordx4 v[10:13], v58, s[46:47] offset:2048
	global_load_dwordx4 v[14:17], v58, s[46:47] offset:3072
	s_lshl_b32 s16, s12, 12
	s_lshr_b32 s17, s12, 20
	s_add_u32 s8, s44, s16
	s_addc_u32 s9, s45, s17
	s_lshl_b32 s16, s12, 6
	s_add_u32 s10, s96, s16
	s_addc_u32 s11, s97, 0
	s_waitcnt lgkmcnt(0)
	s_lshl_b32 s13, s13, 2
	s_lshl_b32 s18, s13, 12
	s_lshl_b32 s19, s13, 6
	global_load_dwordx4 v[20:23], v58, s[8:9]
	global_load_dwordx4 v[24:27], v58, s[8:9] offset:1024
	global_load_dwordx4 v[28:31], v58, s[8:9] offset:2048
	global_load_dwordx4 v[32:35], v58, s[8:9] offset:3072

.Lnorm_a_go:
	v_mul_f32_e32 v60, v21, v21
	v_fmac_f32_e32 v60, v20, v20
	v_fmac_f32_e32 v60, v22, v22
	v_fmac_f32_e32 v60, v23, v23
	v_mul_f32_e32 v61, v25, v25
	v_fmac_f32_e32 v61, v24, v24
	v_fmac_f32_e32 v61, v26, v26
	v_fmac_f32_e32 v61, v27, v27
	v_mul_f32_e32 v62, v29, v29
	v_fmac_f32_e32 v62, v28, v28
	v_fmac_f32_e32 v62, v30, v30
	v_fmac_f32_e32 v62, v31, v31
	v_mul_f32_e32 v63, v33, v33
	v_fmac_f32_e32 v63, v32, v32
	v_fmac_f32_e32 v63, v34, v34
	v_fmac_f32_e32 v63, v35, v35
	v_add_f32_e32 v64, v60, v61
	v_add_f32_e32 v64, v64, v62
	v_add_f32_e32 v64, v64, v63
	ds_bpermute_b32 v65, v52, v64
	s_waitcnt lgkmcnt(0)
	v_add_f32_e32 v64, v64, v65
	ds_bpermute_b32 v65, v53, v64
	s_waitcnt lgkmcnt(0)
	v_add_f32_e32 v64, v64, v65
	ds_bpermute_b32 v65, v54, v64
	s_waitcnt lgkmcnt(0)
	v_add_f32_e32 v64, v64, v65
	ds_bpermute_b32 v65, v55, v64
	s_waitcnt lgkmcnt(0)
	v_add_f32_e32 v64, v64, v65
	ds_bpermute_b32 v65, v56, v64
	s_waitcnt lgkmcnt(0)
	v_add_f32_e32 v64, v64, v65
	ds_bpermute_b32 v65, v57, v64
	s_waitcnt lgkmcnt(0)
	v_add_f32_e32 v64, v64, v65
	v_fmamk_f32 v64, v64, 0x3a800000, v199
	v_cmp_gt_f32_e32 vcc, s73, v64
	v_mul_f32_e32 v65, 0x4b800000, v64
	s_nop 0
	v_cndmask_b32_e32 v64, v64, v65, vcc
	v_rsq_f32_e32 v64, v64
	s_nop 0
	v_mul_f32_e32 v65, 0x45800000, v64
	v_cndmask_b32_e32 v66, v64, v65, vcc
	v_mul_f32_e32 v60, v20, v66
	v_mul_f32_e32 v61, v21, v66
	v_mul_f32_e32 v62, v22, v66
	v_mul_f32_e32 v63, v23, v66
	v_mul_f32_e32 v60, v2, v60
	v_mul_f32_e32 v61, v3, v61
	v_mul_f32_e32 v62, v4, v62
	v_mul_f32_e32 v63, v5, v63
	v_cvt_pk_bf16_f32 v68, v60, v61
	v_cvt_pk_bf16_f32 v69, v62, v63
	global_store_dwordx2 v59, v[68:69], s[10:11]
	v_mul_f32_e32 v60, v24, v66
	v_mul_f32_e32 v61, v25, v66
	v_mul_f32_e32 v62, v26, v66
	v_mul_f32_e32 v63, v27, v66
	v_mul_f32_e32 v60, v6, v60
	v_mul_f32_e32 v61, v7, v61
	v_mul_f32_e32 v62, v8, v62
	v_mul_f32_e32 v63, v9, v63
	v_cvt_pk_bf16_f32 v70, v60, v61
	v_cvt_pk_bf16_f32 v71, v62, v63
	s_add_u32 s16, s10, 0x1000000
	s_addc_u32 s17, s11, 0
	global_store_dwordx2 v59, v[70:71], s[16:17]
	v_mul_f32_e32 v60, v28, v66
	v_mul_f32_e32 v61, v29, v66
	v_mul_f32_e32 v62, v30, v66
	v_mul_f32_e32 v63, v31, v66
	v_mul_f32_e32 v60, v10, v60
	v_mul_f32_e32 v61, v11, v61
	v_mul_f32_e32 v62, v12, v62
	v_mul_f32_e32 v63, v13, v63
	v_cvt_pk_bf16_f32 v72, v60, v61
	v_cvt_pk_bf16_f32 v73, v62, v63
	s_add_u32 s16, s10, 0x2000000
	s_addc_u32 s17, s11, 0
	global_store_dwordx2 v59, v[72:73], s[16:17]
	v_mul_f32_e32 v60, v32, v66
	v_mul_f32_e32 v61, v33, v66
	v_mul_f32_e32 v62, v34, v66
	v_mul_f32_e32 v63, v35, v66
	v_mul_f32_e32 v60, v14, v60
	v_mul_f32_e32 v61, v15, v61
	v_mul_f32_e32 v62, v16, v62
	v_mul_f32_e32 v63, v17, v63
	v_cvt_pk_bf16_f32 v74, v60, v61
	v_cvt_pk_bf16_f32 v75, v62, v63
	s_add_u32 s16, s10, 0x3000000
	s_addc_u32 s17, s11, 0
	global_store_dwordx2 v59, v[74:75], s[16:17]
	s_add_u32 s10, s10, s19
	s_addc_u32 s11, s11, 0
	s_mov_b32 s12, s20
	s_cmp_lt_u32 s12, 0x8000
	s_cbranch_scc0 .LBB0_721

.Lnorm_b_go:
	v_mul_f32_e32 v60, v37, v37
	v_fmac_f32_e32 v60, v36, v36
	v_fmac_f32_e32 v60, v38, v38
	v_fmac_f32_e32 v60, v39, v39
	v_mul_f32_e32 v61, v41, v41
	v_fmac_f32_e32 v61, v40, v40
	v_fmac_f32_e32 v61, v42, v42
	v_fmac_f32_e32 v61, v43, v43
	v_mul_f32_e32 v62, v45, v45
	v_fmac_f32_e32 v62, v44, v44
	v_fmac_f32_e32 v62, v46, v46
	v_fmac_f32_e32 v62, v47, v47
	v_mul_f32_e32 v63, v49, v49
	v_fmac_f32_e32 v63, v48, v48
	v_fmac_f32_e32 v63, v50, v50
	v_fmac_f32_e32 v63, v51, v51
	v_add_f32_e32 v64, v60, v61
	v_add_f32_e32 v64, v64, v62
	v_add_f32_e32 v64, v64, v63
	ds_bpermute_b32 v65, v52, v64
	s_waitcnt lgkmcnt(0)
	v_add_f32_e32 v64, v64, v65
	ds_bpermute_b32 v65, v53, v64
	s_waitcnt lgkmcnt(0)
	v_add_f32_e32 v64, v64, v65
	ds_bpermute_b32 v65, v54, v64
	s_waitcnt lgkmcnt(0)
	v_add_f32_e32 v64, v64, v65
	ds_bpermute_b32 v65, v55, v64
	s_waitcnt lgkmcnt(0)
	v_add_f32_e32 v64, v64, v65
	ds_bpermute_b32 v65, v56, v64
	s_waitcnt lgkmcnt(0)
	v_add_f32_e32 v64, v64, v65
	ds_bpermute_b32 v65, v57, v64
	s_waitcnt lgkmcnt(0)
	v_add_f32_e32 v64, v64, v65
	v_fmamk_f32 v64, v64, 0x3a800000, v199
	v_cmp_gt_f32_e32 vcc, s73, v64
	v_mul_f32_e32 v65, 0x4b800000, v64
	s_nop 0
	v_cndmask_b32_e32 v64, v64, v65, vcc
	v_rsq_f32_e32 v64, v64
	s_nop 0
	v_mul_f32_e32 v65, 0x45800000, v64
	v_cndmask_b32_e32 v66, v64, v65, vcc
	v_mul_f32_e32 v60, v36, v66
	v_mul_f32_e32 v61, v37, v66
	v_mul_f32_e32 v62, v38, v66
	v_mul_f32_e32 v63, v39, v66
	v_mul_f32_e32 v60, v2, v60
	v_mul_f32_e32 v61, v3, v61
	v_mul_f32_e32 v62, v4, v62
	v_mul_f32_e32 v63, v5, v63
	v_cvt_pk_bf16_f32 v68, v60, v61
	v_cvt_pk_bf16_f32 v69, v62, v63
	global_store_dwordx2 v59, v[68:69], s[10:11]
	v_mul_f32_e32 v60, v40, v66
	v_mul_f32_e32 v61, v41, v66
	v_mul_f32_e32 v62, v42, v66
	v_mul_f32_e32 v63, v43, v66
	v_mul_f32_e32 v60, v6, v60
	v_mul_f32_e32 v61, v7, v61
	v_mul_f32_e32 v62, v8, v62
	v_mul_f32_e32 v63, v9, v63
	v_cvt_pk_bf16_f32 v70, v60, v61
	v_cvt_pk_bf16_f32 v71, v62, v63
	s_add_u32 s16, s10, 0x1000000
	s_addc_u32 s17, s11, 0
	global_store_dwordx2 v59, v[70:71], s[16:17]
	v_mul_f32_e32 v60, v44, v66
	v_mul_f32_e32 v61, v45, v66
	v_mul_f32_e32 v62, v46, v66
	v_mul_f32_e32 v63, v47, v66
	v_mul_f32_e32 v60, v10, v60
	v_mul_f32_e32 v61, v11, v61
	v_mul_f32_e32 v62, v12, v62
	v_mul_f32_e32 v63, v13, v63
	v_cvt_pk_bf16_f32 v72, v60, v61
	v_cvt_pk_bf16_f32 v73, v62, v63
	s_add_u32 s16, s10, 0x2000000
	s_addc_u32 s17, s11, 0
	global_store_dwordx2 v59, v[72:73], s[16:17]
	v_mul_f32_e32 v60, v48, v66
	v_mul_f32_e32 v61, v49, v66
	v_mul_f32_e32 v62, v50, v66
	v_mul_f32_e32 v63, v51, v66
	v_mul_f32_e32 v60, v14, v60
	v_mul_f32_e32 v61, v15, v61
	v_mul_f32_e32 v62, v16, v62
	v_mul_f32_e32 v63, v17, v63
	v_cvt_pk_bf16_f32 v74, v60, v61
	v_cvt_pk_bf16_f32 v75, v62, v63
	s_add_u32 s16, s10, 0x3000000
	s_addc_u32 s17, s11, 0
	global_store_dwordx2 v59, v[74:75], s[16:17]
	s_add_u32 s10, s10, s19
	s_addc_u32 s11, s11, 0
	s_mov_b32 s12, s20
	s_cmp_lt_u32 s12, 0x8000
	s_cbranch_scc0 .LBB0_721
	s_branch .Lnorm_a
